# split44 + all s_setprio removed from the 7 GEMM K-loops (no wave priority toggling in the mainloop)
# speedup vs baseline: 1.0129x; 1.0039x over previous
.LBB0_140:
	s_add_u32 s2, s22, 0xfff80080
	s_addc_u32 s20, s23, -1
	s_add_i32 s45, 0, 0x10000
	s_cmp_eq_u32 s44, 28
	s_cselect_b32 s25, s15, s20
	s_cselect_b32 s24, s40, s2
	v_add_u32_e32 v144, s45, v148
	s_cselect_b32 s21, s13, s43
	s_cselect_b32 s20, s41, s42
	s_add_u32 s100, s22, 0xfff80000
	s_addc_u32 s101, s23, -1
	s_add_i32 s2, 0, 0x14000
	ds_read_b128 v[140:143], v144
	ds_read_b128 v[152:155], v144 offset:1024
	ds_read_b128 v[156:159], v144 offset:2048
	ds_read_b128 v[160:163], v144 offset:3072
	v_add_u32_e32 v144, s2, v148
	ds_read_b128 v[164:167], v144
	ds_read_b128 v[168:171], v144 offset:1024
	ds_read_b128 v[172:175], v144 offset:2048
	ds_read_b128 v[176:179], v144 offset:3072
	s_add_i32 m0, s29, 0xc000
	ds_read_b128 v[180:183], v151
	ds_read_b128 v[184:187], v151 offset:1024
	ds_read_b128 v[188:191], v151 offset:2048
	ds_read_b128 v[192:195], v151 offset:3072
	ds_read_b128 v[206:209], v151 offset:4096
	ds_read_b128 v[210:213], v151 offset:5120
	ds_read_b128 v[214:217], v151 offset:6144
	ds_read_b128 v[218:221], v151 offset:7168
	s_mov_b32 m0, s35
	s_nop 0
	global_load_lds_dwordx4 v136, s[100:101]
	s_mov_b32 m0, s36
	s_nop 0
	global_load_lds_dwordx4 v138, s[100:101]
	s_add_i32 m0, s29, 0xc000
	s_nop 0
	global_load_lds_dwordx4 v136, s[22:23]
	s_add_i32 m0, s29, 0xe000
	s_nop 0
	global_load_lds_dwordx4 v138, s[22:23]
	s_waitcnt vmcnt(8)
	s_waitcnt lgkmcnt(0)
	s_barrier
	s_waitcnt lgkmcnt(0)
	v_mfma_f32_16x16x32_bf16 v[126:129], v[140:143], v[180:183], v[126:129]
	v_mfma_f32_16x16x32_bf16 v[122:125], v[156:159], v[180:183], v[122:125]
	v_mfma_f32_16x16x32_bf16 v[110:113], v[140:143], v[188:191], v[110:113]
	v_mfma_f32_16x16x32_bf16 v[106:109], v[156:159], v[188:191], v[106:109]
	v_mfma_f32_16x16x32_bf16 v[94:97], v[140:143], v[206:209], v[94:97]
	v_mfma_f32_16x16x32_bf16 v[90:93], v[156:159], v[206:209], v[90:93]
	v_mfma_f32_16x16x32_bf16 v[78:81], v[140:143], v[214:217], v[78:81]
	v_mfma_f32_16x16x32_bf16 v[74:77], v[156:159], v[214:217], v[74:77]
	v_mfma_f32_16x16x32_bf16 v[126:129], v[152:155], v[184:187], v[126:129]
	v_mfma_f32_16x16x32_bf16 v[122:125], v[160:163], v[184:187], v[122:125]
	v_mfma_f32_16x16x32_bf16 v[110:113], v[152:155], v[192:195], v[110:113]
	v_mfma_f32_16x16x32_bf16 v[106:109], v[160:163], v[192:195], v[106:109]
	v_mfma_f32_16x16x32_bf16 v[94:97], v[152:155], v[210:213], v[94:97]
	v_mfma_f32_16x16x32_bf16 v[90:93], v[160:163], v[210:213], v[90:93]
	v_mfma_f32_16x16x32_bf16 v[78:81], v[152:155], v[218:221], v[78:81]
	v_mfma_f32_16x16x32_bf16 v[74:77], v[160:163], v[218:221], v[74:77]
	v_mfma_f32_16x16x32_bf16 v[118:121], v[164:167], v[180:183], v[118:121]
	v_mfma_f32_16x16x32_bf16 v[114:117], v[172:175], v[180:183], v[114:117]
	v_mfma_f32_16x16x32_bf16 v[102:105], v[164:167], v[188:191], v[102:105]
	v_mfma_f32_16x16x32_bf16 v[98:101], v[172:175], v[188:191], v[98:101]
	v_mfma_f32_16x16x32_bf16 v[86:89], v[164:167], v[206:209], v[86:89]
	v_mfma_f32_16x16x32_bf16 v[82:85], v[172:175], v[206:209], v[82:85]
	v_mfma_f32_16x16x32_bf16 v[70:73], v[164:167], v[214:217], v[70:73]
	v_mfma_f32_16x16x32_bf16 v[66:69], v[172:175], v[214:217], v[66:69]
	v_mfma_f32_16x16x32_bf16 v[118:121], v[168:171], v[184:187], v[118:121]
	v_mfma_f32_16x16x32_bf16 v[114:117], v[176:179], v[184:187], v[114:117]
	v_mfma_f32_16x16x32_bf16 v[102:105], v[168:171], v[192:195], v[102:105]
	v_mfma_f32_16x16x32_bf16 v[98:101], v[176:179], v[192:195], v[98:101]
	v_mfma_f32_16x16x32_bf16 v[86:89], v[168:171], v[210:213], v[86:89]
	v_mfma_f32_16x16x32_bf16 v[82:85], v[176:179], v[210:213], v[82:85]
	v_mfma_f32_16x16x32_bf16 v[70:73], v[168:171], v[218:221], v[70:73]
	v_mfma_f32_16x16x32_bf16 v[66:69], v[176:179], v[218:221], v[66:69]
	s_barrier
	s_add_u32 s46, s20, 0x80000
	s_addc_u32 s47, s21, 0
	s_add_i32 s45, s45, s28
	s_mov_b32 m0, s45
	ds_read_b128 v[180:183], v151 offset:16384
	ds_read_b128 v[184:187], v151 offset:17408
	ds_read_b128 v[188:191], v151 offset:18432
	ds_read_b128 v[192:195], v151 offset:19456
	ds_read_b128 v[206:209], v151 offset:20480
	ds_read_b128 v[210:213], v151 offset:21504
	ds_read_b128 v[214:217], v151 offset:22528
	ds_read_b128 v[218:221], v151 offset:23552
	global_load_lds_dwordx4 v0, s[20:21]
	s_add_i32 m0, s45, 0x2000
	s_add_i32 s2, s2, s28
	global_load_lds_dwordx4 v130, s[20:21]
	s_mov_b32 m0, s2
	s_nop 0
	global_load_lds_dwordx4 v0, s[46:47]
	s_add_i32 m0, s2, 0x2000
	s_nop 0
	global_load_lds_dwordx4 v130, s[46:47]
	s_waitcnt vmcnt(6)
	s_waitcnt lgkmcnt(0)
	s_barrier
	s_waitcnt lgkmcnt(0)
	v_mfma_f32_16x16x32_bf16 v[62:65], v[140:143], v[180:183], v[62:65]
	v_mfma_f32_16x16x32_bf16 v[58:61], v[156:159], v[180:183], v[58:61]
	v_mfma_f32_16x16x32_bf16 v[46:49], v[140:143], v[188:191], v[46:49]
	v_mfma_f32_16x16x32_bf16 v[42:45], v[156:159], v[188:191], v[42:45]
	v_mfma_f32_16x16x32_bf16 v[30:33], v[140:143], v[206:209], v[30:33]
	v_mfma_f32_16x16x32_bf16 v[26:29], v[156:159], v[206:209], v[26:29]
	v_mfma_f32_16x16x32_bf16 v[14:17], v[140:143], v[214:217], v[14:17]
	v_mfma_f32_16x16x32_bf16 v[10:13], v[156:159], v[214:217], v[10:13]
	v_mfma_f32_16x16x32_bf16 v[62:65], v[152:155], v[184:187], v[62:65]
	v_mfma_f32_16x16x32_bf16 v[58:61], v[160:163], v[184:187], v[58:61]
	v_mfma_f32_16x16x32_bf16 v[46:49], v[152:155], v[192:195], v[46:49]
	v_mfma_f32_16x16x32_bf16 v[42:45], v[160:163], v[192:195], v[42:45]
	v_mfma_f32_16x16x32_bf16 v[30:33], v[152:155], v[210:213], v[30:33]
	v_mfma_f32_16x16x32_bf16 v[26:29], v[160:163], v[210:213], v[26:29]
	v_mfma_f32_16x16x32_bf16 v[14:17], v[152:155], v[218:221], v[14:17]
	v_mfma_f32_16x16x32_bf16 v[10:13], v[160:163], v[218:221], v[10:13]
	v_mfma_f32_16x16x32_bf16 v[54:57], v[164:167], v[180:183], v[54:57]
	v_mfma_f32_16x16x32_bf16 v[50:53], v[172:175], v[180:183], v[50:53]
	v_mfma_f32_16x16x32_bf16 v[38:41], v[164:167], v[188:191], v[38:41]
	v_mfma_f32_16x16x32_bf16 v[34:37], v[172:175], v[188:191], v[34:37]
	v_mfma_f32_16x16x32_bf16 v[22:25], v[164:167], v[206:209], v[22:25]
	v_mfma_f32_16x16x32_bf16 v[18:21], v[172:175], v[206:209], v[18:21]
	v_mfma_f32_16x16x32_bf16 v[6:9], v[164:167], v[214:217], v[6:9]
	v_mfma_f32_16x16x32_bf16 v[2:5], v[172:175], v[214:217], v[2:5]
	v_mfma_f32_16x16x32_bf16 v[54:57], v[168:171], v[184:187], v[54:57]
	v_mfma_f32_16x16x32_bf16 v[50:53], v[176:179], v[184:187], v[50:53]
	v_mfma_f32_16x16x32_bf16 v[38:41], v[168:171], v[192:195], v[38:41]
	v_mfma_f32_16x16x32_bf16 v[34:37], v[176:179], v[192:195], v[34:37]
	v_mfma_f32_16x16x32_bf16 v[22:25], v[168:171], v[210:213], v[22:25]
	v_mfma_f32_16x16x32_bf16 v[18:21], v[176:179], v[210:213], v[18:21]
	v_mfma_f32_16x16x32_bf16 v[6:9], v[168:171], v[218:221], v[6:9]
	v_mfma_f32_16x16x32_bf16 v[2:5], v[176:179], v[218:221], v[2:5]
	s_barrier
	s_add_u32 s24, s24, 0x80000
	s_addc_u32 s25, s25, 0
	s_add_u32 s100, s24, 0xfff80000
	s_addc_u32 s101, s25, -1
	s_add_i32 s2, 0, 0x18000
	s_add_i32 s45, 0, 0x1c000
	v_add_u32_e32 v160, s2, v148
	v_add_u32_e32 v176, s45, v148
	ds_read_b128 v[140:143], v160
	ds_read_b128 v[152:155], v160 offset:1024
	ds_read_b128 v[156:159], v160 offset:2048
	ds_read_b128 v[160:163], v160 offset:3072
	ds_read_b128 v[164:167], v176
	ds_read_b128 v[168:171], v176 offset:1024
	ds_read_b128 v[172:175], v176 offset:2048
	ds_read_b128 v[176:179], v176 offset:3072
	s_mov_b32 m0, s31
	ds_read_b128 v[180:183], v151 offset:32768
	ds_read_b128 v[184:187], v151 offset:33792
	ds_read_b128 v[188:191], v151 offset:34816
	ds_read_b128 v[192:195], v151 offset:35840
	ds_read_b128 v[206:209], v151 offset:36864
	ds_read_b128 v[210:213], v151 offset:37888
	ds_read_b128 v[214:217], v151 offset:38912
	ds_read_b128 v[218:221], v151 offset:39936
	s_mov_b32 m0, s29
	s_nop 0
	global_load_lds_dwordx4 v134, s[100:101]
	s_mov_b32 m0, s30
	s_nop 0
	global_load_lds_dwordx4 v132, s[100:101]
	s_mov_b32 m0, s31
	s_nop 0
	global_load_lds_dwordx4 v134, s[24:25]
	s_mov_b32 m0, s33
	s_nop 0
	global_load_lds_dwordx4 v132, s[24:25]
	s_waitcnt vmcnt(8)
	s_waitcnt lgkmcnt(0)
	s_barrier
	s_waitcnt lgkmcnt(0)
	v_mfma_f32_16x16x32_bf16 v[126:129], v[140:143], v[180:183], v[126:129]
	v_mfma_f32_16x16x32_bf16 v[122:125], v[156:159], v[180:183], v[122:125]
	v_mfma_f32_16x16x32_bf16 v[110:113], v[140:143], v[188:191], v[110:113]
	v_mfma_f32_16x16x32_bf16 v[106:109], v[156:159], v[188:191], v[106:109]
	v_mfma_f32_16x16x32_bf16 v[94:97], v[140:143], v[206:209], v[94:97]
	v_mfma_f32_16x16x32_bf16 v[90:93], v[156:159], v[206:209], v[90:93]
	v_mfma_f32_16x16x32_bf16 v[78:81], v[140:143], v[214:217], v[78:81]
	v_mfma_f32_16x16x32_bf16 v[74:77], v[156:159], v[214:217], v[74:77]
	v_mfma_f32_16x16x32_bf16 v[126:129], v[152:155], v[184:187], v[126:129]
	v_mfma_f32_16x16x32_bf16 v[122:125], v[160:163], v[184:187], v[122:125]
	v_mfma_f32_16x16x32_bf16 v[110:113], v[152:155], v[192:195], v[110:113]
	v_mfma_f32_16x16x32_bf16 v[106:109], v[160:163], v[192:195], v[106:109]
	v_mfma_f32_16x16x32_bf16 v[94:97], v[152:155], v[210:213], v[94:97]
	v_mfma_f32_16x16x32_bf16 v[90:93], v[160:163], v[210:213], v[90:93]
	v_mfma_f32_16x16x32_bf16 v[78:81], v[152:155], v[218:221], v[78:81]
	v_mfma_f32_16x16x32_bf16 v[74:77], v[160:163], v[218:221], v[74:77]
	v_mfma_f32_16x16x32_bf16 v[118:121], v[164:167], v[180:183], v[118:121]
	v_mfma_f32_16x16x32_bf16 v[114:117], v[172:175], v[180:183], v[114:117]
	v_mfma_f32_16x16x32_bf16 v[102:105], v[164:167], v[188:191], v[102:105]
	v_mfma_f32_16x16x32_bf16 v[98:101], v[172:175], v[188:191], v[98:101]
	v_mfma_f32_16x16x32_bf16 v[86:89], v[164:167], v[206:209], v[86:89]
	v_mfma_f32_16x16x32_bf16 v[82:85], v[172:175], v[206:209], v[82:85]
	v_mfma_f32_16x16x32_bf16 v[70:73], v[164:167], v[214:217], v[70:73]
	v_mfma_f32_16x16x32_bf16 v[66:69], v[172:175], v[214:217], v[66:69]
	v_mfma_f32_16x16x32_bf16 v[118:121], v[168:171], v[184:187], v[118:121]
	v_mfma_f32_16x16x32_bf16 v[114:117], v[176:179], v[184:187], v[114:117]
	v_mfma_f32_16x16x32_bf16 v[102:105], v[168:171], v[192:195], v[102:105]
	v_mfma_f32_16x16x32_bf16 v[98:101], v[176:179], v[192:195], v[98:101]
	v_mfma_f32_16x16x32_bf16 v[86:89], v[168:171], v[210:213], v[86:89]
	v_mfma_f32_16x16x32_bf16 v[82:85], v[176:179], v[210:213], v[82:85]
	v_mfma_f32_16x16x32_bf16 v[70:73], v[168:171], v[218:221], v[70:73]
	v_mfma_f32_16x16x32_bf16 v[66:69], v[176:179], v[218:221], v[66:69]
	s_barrier
	s_add_u32 s20, s20, 0x80080
	s_addc_u32 s21, s21, 0
	s_add_u32 s46, s46, 0xfff80080
	s_addc_u32 s47, s47, -1
	s_add_i32 s2, s2, s28
	s_mov_b32 m0, s2
	ds_read_b128 v[180:183], v151 offset:49152
	ds_read_b128 v[184:187], v151 offset:50176
	ds_read_b128 v[188:191], v151 offset:51200
	ds_read_b128 v[192:195], v151 offset:52224
	ds_read_b128 v[206:209], v151 offset:53248
	ds_read_b128 v[210:213], v151 offset:54272
	ds_read_b128 v[214:217], v151 offset:55296
	ds_read_b128 v[218:221], v151 offset:56320
	global_load_lds_dwordx4 v0, s[46:47]
	s_add_i32 m0, s2, 0x2000
	s_add_i32 s2, s45, s28
	global_load_lds_dwordx4 v130, s[46:47]
	s_mov_b32 m0, s2
	s_nop 0
	global_load_lds_dwordx4 v0, s[20:21]
	s_add_i32 m0, s2, 0x2000
	s_nop 0
	global_load_lds_dwordx4 v130, s[20:21]
	s_waitcnt vmcnt(6)
	s_waitcnt lgkmcnt(0)
	s_barrier
	s_waitcnt lgkmcnt(0)
	v_mfma_f32_16x16x32_bf16 v[62:65], v[140:143], v[180:183], v[62:65]
	v_mfma_f32_16x16x32_bf16 v[58:61], v[156:159], v[180:183], v[58:61]
	v_mfma_f32_16x16x32_bf16 v[46:49], v[140:143], v[188:191], v[46:49]
	v_mfma_f32_16x16x32_bf16 v[42:45], v[156:159], v[188:191], v[42:45]
	v_mfma_f32_16x16x32_bf16 v[30:33], v[140:143], v[206:209], v[30:33]
	v_mfma_f32_16x16x32_bf16 v[26:29], v[156:159], v[206:209], v[26:29]
	v_mfma_f32_16x16x32_bf16 v[14:17], v[140:143], v[214:217], v[14:17]
	v_mfma_f32_16x16x32_bf16 v[10:13], v[156:159], v[214:217], v[10:13]
	v_mfma_f32_16x16x32_bf16 v[62:65], v[152:155], v[184:187], v[62:65]
	v_mfma_f32_16x16x32_bf16 v[58:61], v[160:163], v[184:187], v[58:61]
	v_mfma_f32_16x16x32_bf16 v[46:49], v[152:155], v[192:195], v[46:49]
	v_mfma_f32_16x16x32_bf16 v[42:45], v[160:163], v[192:195], v[42:45]
	v_mfma_f32_16x16x32_bf16 v[30:33], v[152:155], v[210:213], v[30:33]
	v_mfma_f32_16x16x32_bf16 v[26:29], v[160:163], v[210:213], v[26:29]
	v_mfma_f32_16x16x32_bf16 v[14:17], v[152:155], v[218:221], v[14:17]
	v_mfma_f32_16x16x32_bf16 v[10:13], v[160:163], v[218:221], v[10:13]
	v_mfma_f32_16x16x32_bf16 v[54:57], v[164:167], v[180:183], v[54:57]
	v_mfma_f32_16x16x32_bf16 v[50:53], v[172:175], v[180:183], v[50:53]
	v_mfma_f32_16x16x32_bf16 v[38:41], v[164:167], v[188:191], v[38:41]
	v_mfma_f32_16x16x32_bf16 v[34:37], v[172:175], v[188:191], v[34:37]
	v_mfma_f32_16x16x32_bf16 v[22:25], v[164:167], v[206:209], v[22:25]
	v_mfma_f32_16x16x32_bf16 v[18:21], v[172:175], v[206:209], v[18:21]
	v_mfma_f32_16x16x32_bf16 v[6:9], v[164:167], v[214:217], v[6:9]
	v_mfma_f32_16x16x32_bf16 v[2:5], v[172:175], v[214:217], v[2:5]
	v_mfma_f32_16x16x32_bf16 v[54:57], v[168:171], v[184:187], v[54:57]
	v_mfma_f32_16x16x32_bf16 v[50:53], v[176:179], v[184:187], v[50:53]
	v_mfma_f32_16x16x32_bf16 v[38:41], v[168:171], v[192:195], v[38:41]
	v_mfma_f32_16x16x32_bf16 v[34:37], v[176:179], v[192:195], v[34:37]
	v_mfma_f32_16x16x32_bf16 v[22:25], v[168:171], v[210:213], v[22:25]
	v_mfma_f32_16x16x32_bf16 v[18:21], v[176:179], v[210:213], v[18:21]
	v_mfma_f32_16x16x32_bf16 v[6:9], v[168:171], v[218:221], v[6:9]
	v_mfma_f32_16x16x32_bf16 v[2:5], v[176:179], v[218:221], v[2:5]
	s_barrier
	s_add_i32 s44, s44, 2
	s_add_u32 s22, s22, 0x100
	s_addc_u32 s23, s23, 0
	s_add_u32 s42, s42, 0x100
	s_addc_u32 s43, s43, 0
	s_cmp_gt_u32 s44, 29
	s_cbranch_scc0 .LBB0_140
	s_nop 0
	s_and_b64 vcc, exec, s[10:11]
	s_cbranch_vccz .LBB0_143
	s_barrier

.LBB0_168:
	s_add_u32 s2, s26, 0xfff80080
	s_addc_u32 s24, s27, -1
	s_add_i32 s50, 0, 0x10000
	s_cmp_eq_u32 s49, 28
	s_cselect_b32 s29, s19, s24
	s_cselect_b32 s28, s44, s2
	v_add_u32_e32 v144, s50, v152
	s_cselect_b32 s25, s17, s47
	s_cselect_b32 s24, s45, s46
	s_add_u32 s100, s26, 0xfff80000
	s_addc_u32 s101, s27, -1
	s_add_i32 s2, 0, 0x14000
	ds_read_b128 v[140:143], v144
	ds_read_b128 v[148:151], v144 offset:1024
	ds_read_b128 v[156:159], v144 offset:2048
	ds_read_b128 v[160:163], v144 offset:3072
	v_add_u32_e32 v144, s2, v152
	ds_read_b128 v[164:167], v144
	ds_read_b128 v[168:171], v144 offset:1024
	ds_read_b128 v[172:175], v144 offset:2048
	ds_read_b128 v[176:179], v144 offset:3072
	s_add_i32 m0, s33, 0xc000
	ds_read_b128 v[180:183], v155
	ds_read_b128 v[184:187], v155 offset:1024
	ds_read_b128 v[188:191], v155 offset:2048
	ds_read_b128 v[192:195], v155 offset:3072
	ds_read_b128 v[206:209], v155 offset:4096
	ds_read_b128 v[210:213], v155 offset:5120
	ds_read_b128 v[214:217], v155 offset:6144
	ds_read_b128 v[218:221], v155 offset:7168
	s_mov_b32 m0, s39
	s_nop 0
	global_load_lds_dwordx4 v136, s[100:101]
	s_mov_b32 m0, s40
	s_nop 0
	global_load_lds_dwordx4 v138, s[100:101]
	s_add_i32 m0, s33, 0xc000
	s_nop 0
	global_load_lds_dwordx4 v136, s[26:27]
	s_add_i32 m0, s33, 0xe000
	s_nop 0
	global_load_lds_dwordx4 v138, s[26:27]
	s_waitcnt vmcnt(8)
	s_waitcnt lgkmcnt(0)
	s_barrier
	s_waitcnt lgkmcnt(0)
	v_mfma_f32_16x16x32_bf16 v[122:125], v[140:143], v[180:183], v[122:125]
	v_mfma_f32_16x16x32_bf16 v[114:117], v[156:159], v[180:183], v[114:117]
	v_mfma_f32_16x16x32_bf16 v[106:109], v[140:143], v[188:191], v[106:109]
	v_mfma_f32_16x16x32_bf16 v[98:101], v[156:159], v[188:191], v[98:101]
	v_mfma_f32_16x16x32_bf16 v[90:93], v[140:143], v[206:209], v[90:93]
	v_mfma_f32_16x16x32_bf16 v[82:85], v[156:159], v[206:209], v[82:85]
	v_mfma_f32_16x16x32_bf16 v[74:77], v[140:143], v[214:217], v[74:77]
	v_mfma_f32_16x16x32_bf16 v[66:69], v[156:159], v[214:217], v[66:69]
	v_mfma_f32_16x16x32_bf16 v[122:125], v[148:151], v[184:187], v[122:125]
	v_mfma_f32_16x16x32_bf16 v[114:117], v[160:163], v[184:187], v[114:117]
	v_mfma_f32_16x16x32_bf16 v[106:109], v[148:151], v[192:195], v[106:109]
	v_mfma_f32_16x16x32_bf16 v[98:101], v[160:163], v[192:195], v[98:101]
	v_mfma_f32_16x16x32_bf16 v[90:93], v[148:151], v[210:213], v[90:93]
	v_mfma_f32_16x16x32_bf16 v[82:85], v[160:163], v[210:213], v[82:85]
	v_mfma_f32_16x16x32_bf16 v[74:77], v[148:151], v[218:221], v[74:77]
	v_mfma_f32_16x16x32_bf16 v[66:69], v[160:163], v[218:221], v[66:69]
	v_mfma_f32_16x16x32_bf16 v[126:129], v[164:167], v[180:183], v[126:129]
	v_mfma_f32_16x16x32_bf16 v[118:121], v[172:175], v[180:183], v[118:121]
	v_mfma_f32_16x16x32_bf16 v[110:113], v[164:167], v[188:191], v[110:113]
	v_mfma_f32_16x16x32_bf16 v[102:105], v[172:175], v[188:191], v[102:105]
	v_mfma_f32_16x16x32_bf16 v[94:97], v[164:167], v[206:209], v[94:97]
	v_mfma_f32_16x16x32_bf16 v[86:89], v[172:175], v[206:209], v[86:89]
	v_mfma_f32_16x16x32_bf16 v[78:81], v[164:167], v[214:217], v[78:81]
	v_mfma_f32_16x16x32_bf16 v[70:73], v[172:175], v[214:217], v[70:73]
	v_mfma_f32_16x16x32_bf16 v[126:129], v[168:171], v[184:187], v[126:129]
	v_mfma_f32_16x16x32_bf16 v[118:121], v[176:179], v[184:187], v[118:121]
	v_mfma_f32_16x16x32_bf16 v[110:113], v[168:171], v[192:195], v[110:113]
	v_mfma_f32_16x16x32_bf16 v[102:105], v[176:179], v[192:195], v[102:105]
	v_mfma_f32_16x16x32_bf16 v[94:97], v[168:171], v[210:213], v[94:97]
	v_mfma_f32_16x16x32_bf16 v[86:89], v[176:179], v[210:213], v[86:89]
	v_mfma_f32_16x16x32_bf16 v[78:81], v[168:171], v[218:221], v[78:81]
	v_mfma_f32_16x16x32_bf16 v[70:73], v[176:179], v[218:221], v[70:73]
	s_barrier
	s_add_u32 s52, s24, 0x80000
	s_addc_u32 s53, s25, 0
	s_add_i32 s50, s50, s35
	s_mov_b32 m0, s50
	ds_read_b128 v[180:183], v155 offset:16384
	ds_read_b128 v[184:187], v155 offset:17408
	ds_read_b128 v[188:191], v155 offset:18432
	ds_read_b128 v[192:195], v155 offset:19456
	ds_read_b128 v[206:209], v155 offset:20480
	ds_read_b128 v[210:213], v155 offset:21504
	ds_read_b128 v[214:217], v155 offset:22528
	ds_read_b128 v[218:221], v155 offset:23552
	global_load_lds_dwordx4 v0, s[24:25]
	s_add_i32 m0, s50, 0x2000
	s_add_i32 s2, s2, s35
	global_load_lds_dwordx4 v130, s[24:25]
	s_mov_b32 m0, s2
	s_nop 0
	global_load_lds_dwordx4 v0, s[52:53]
	s_add_i32 m0, s2, 0x2000
	s_nop 0
	global_load_lds_dwordx4 v130, s[52:53]
	s_waitcnt vmcnt(6)
	s_waitcnt lgkmcnt(0)
	s_barrier
	s_waitcnt lgkmcnt(0)
	v_mfma_f32_16x16x32_bf16 v[58:61], v[140:143], v[180:183], v[58:61]
	v_mfma_f32_16x16x32_bf16 v[50:53], v[156:159], v[180:183], v[50:53]
	v_mfma_f32_16x16x32_bf16 v[42:45], v[140:143], v[188:191], v[42:45]
	v_mfma_f32_16x16x32_bf16 v[34:37], v[156:159], v[188:191], v[34:37]
	v_mfma_f32_16x16x32_bf16 v[26:29], v[140:143], v[206:209], v[26:29]
	v_mfma_f32_16x16x32_bf16 v[18:21], v[156:159], v[206:209], v[18:21]
	v_mfma_f32_16x16x32_bf16 v[10:13], v[140:143], v[214:217], v[10:13]
	v_mfma_f32_16x16x32_bf16 v[6:9], v[156:159], v[214:217], v[6:9]
	v_mfma_f32_16x16x32_bf16 v[58:61], v[148:151], v[184:187], v[58:61]
	v_mfma_f32_16x16x32_bf16 v[50:53], v[160:163], v[184:187], v[50:53]
	v_mfma_f32_16x16x32_bf16 v[42:45], v[148:151], v[192:195], v[42:45]
	v_mfma_f32_16x16x32_bf16 v[34:37], v[160:163], v[192:195], v[34:37]
	v_mfma_f32_16x16x32_bf16 v[26:29], v[148:151], v[210:213], v[26:29]
	v_mfma_f32_16x16x32_bf16 v[18:21], v[160:163], v[210:213], v[18:21]
	v_mfma_f32_16x16x32_bf16 v[10:13], v[148:151], v[218:221], v[10:13]
	v_mfma_f32_16x16x32_bf16 v[6:9], v[160:163], v[218:221], v[6:9]
	v_mfma_f32_16x16x32_bf16 v[62:65], v[164:167], v[180:183], v[62:65]
	v_mfma_f32_16x16x32_bf16 v[54:57], v[172:175], v[180:183], v[54:57]
	v_mfma_f32_16x16x32_bf16 v[46:49], v[164:167], v[188:191], v[46:49]
	v_mfma_f32_16x16x32_bf16 v[38:41], v[172:175], v[188:191], v[38:41]
	v_mfma_f32_16x16x32_bf16 v[30:33], v[164:167], v[206:209], v[30:33]
	v_mfma_f32_16x16x32_bf16 v[22:25], v[172:175], v[206:209], v[22:25]
	v_mfma_f32_16x16x32_bf16 v[14:17], v[164:167], v[214:217], v[14:17]
	v_mfma_f32_16x16x32_bf16 v[2:5], v[172:175], v[214:217], v[2:5]
	v_mfma_f32_16x16x32_bf16 v[62:65], v[168:171], v[184:187], v[62:65]
	v_mfma_f32_16x16x32_bf16 v[54:57], v[176:179], v[184:187], v[54:57]
	v_mfma_f32_16x16x32_bf16 v[46:49], v[168:171], v[192:195], v[46:49]
	v_mfma_f32_16x16x32_bf16 v[38:41], v[176:179], v[192:195], v[38:41]
	v_mfma_f32_16x16x32_bf16 v[30:33], v[168:171], v[210:213], v[30:33]
	v_mfma_f32_16x16x32_bf16 v[22:25], v[176:179], v[210:213], v[22:25]
	v_mfma_f32_16x16x32_bf16 v[14:17], v[168:171], v[218:221], v[14:17]
	v_mfma_f32_16x16x32_bf16 v[2:5], v[176:179], v[218:221], v[2:5]
	s_barrier
	s_add_u32 s28, s28, 0x80000
	s_addc_u32 s29, s29, 0
	s_add_u32 s100, s28, 0xfff80000
	s_addc_u32 s101, s29, -1
	s_add_i32 s2, 0, 0x18000
	s_add_i32 s50, 0, 0x1c000
	v_add_u32_e32 v160, s2, v152
	v_add_u32_e32 v176, s50, v152
	ds_read_b128 v[140:143], v160
	ds_read_b128 v[148:151], v160 offset:1024
	ds_read_b128 v[156:159], v160 offset:2048
	ds_read_b128 v[160:163], v160 offset:3072
	ds_read_b128 v[164:167], v176
	ds_read_b128 v[168:171], v176 offset:1024
	ds_read_b128 v[172:175], v176 offset:2048
	ds_read_b128 v[176:179], v176 offset:3072
	s_mov_b32 m0, s37
	ds_read_b128 v[180:183], v155 offset:32768
	ds_read_b128 v[184:187], v155 offset:33792
	ds_read_b128 v[188:191], v155 offset:34816
	ds_read_b128 v[192:195], v155 offset:35840
	ds_read_b128 v[206:209], v155 offset:36864
	ds_read_b128 v[210:213], v155 offset:37888
	ds_read_b128 v[214:217], v155 offset:38912
	ds_read_b128 v[218:221], v155 offset:39936
	s_mov_b32 m0, s33
	s_nop 0
	global_load_lds_dwordx4 v134, s[100:101]
	s_mov_b32 m0, s36
	s_nop 0
	global_load_lds_dwordx4 v132, s[100:101]
	s_mov_b32 m0, s37
	s_nop 0
	global_load_lds_dwordx4 v134, s[28:29]
	s_mov_b32 m0, s38
	s_nop 0
	global_load_lds_dwordx4 v132, s[28:29]
	s_waitcnt vmcnt(8)
	s_waitcnt lgkmcnt(0)
	s_barrier
	s_waitcnt lgkmcnt(0)
	v_mfma_f32_16x16x32_bf16 v[122:125], v[140:143], v[180:183], v[122:125]
	v_mfma_f32_16x16x32_bf16 v[114:117], v[156:159], v[180:183], v[114:117]
	v_mfma_f32_16x16x32_bf16 v[106:109], v[140:143], v[188:191], v[106:109]
	v_mfma_f32_16x16x32_bf16 v[98:101], v[156:159], v[188:191], v[98:101]
	v_mfma_f32_16x16x32_bf16 v[90:93], v[140:143], v[206:209], v[90:93]
	v_mfma_f32_16x16x32_bf16 v[82:85], v[156:159], v[206:209], v[82:85]
	v_mfma_f32_16x16x32_bf16 v[74:77], v[140:143], v[214:217], v[74:77]
	v_mfma_f32_16x16x32_bf16 v[66:69], v[156:159], v[214:217], v[66:69]
	v_mfma_f32_16x16x32_bf16 v[122:125], v[148:151], v[184:187], v[122:125]
	v_mfma_f32_16x16x32_bf16 v[114:117], v[160:163], v[184:187], v[114:117]
	v_mfma_f32_16x16x32_bf16 v[106:109], v[148:151], v[192:195], v[106:109]
	v_mfma_f32_16x16x32_bf16 v[98:101], v[160:163], v[192:195], v[98:101]
	v_mfma_f32_16x16x32_bf16 v[90:93], v[148:151], v[210:213], v[90:93]
	v_mfma_f32_16x16x32_bf16 v[82:85], v[160:163], v[210:213], v[82:85]
	v_mfma_f32_16x16x32_bf16 v[74:77], v[148:151], v[218:221], v[74:77]
	v_mfma_f32_16x16x32_bf16 v[66:69], v[160:163], v[218:221], v[66:69]
	v_mfma_f32_16x16x32_bf16 v[126:129], v[164:167], v[180:183], v[126:129]
	v_mfma_f32_16x16x32_bf16 v[118:121], v[172:175], v[180:183], v[118:121]
	v_mfma_f32_16x16x32_bf16 v[110:113], v[164:167], v[188:191], v[110:113]
	v_mfma_f32_16x16x32_bf16 v[102:105], v[172:175], v[188:191], v[102:105]
	v_mfma_f32_16x16x32_bf16 v[94:97], v[164:167], v[206:209], v[94:97]
	v_mfma_f32_16x16x32_bf16 v[86:89], v[172:175], v[206:209], v[86:89]
	v_mfma_f32_16x16x32_bf16 v[78:81], v[164:167], v[214:217], v[78:81]
	v_mfma_f32_16x16x32_bf16 v[70:73], v[172:175], v[214:217], v[70:73]
	v_mfma_f32_16x16x32_bf16 v[126:129], v[168:171], v[184:187], v[126:129]
	v_mfma_f32_16x16x32_bf16 v[118:121], v[176:179], v[184:187], v[118:121]
	v_mfma_f32_16x16x32_bf16 v[110:113], v[168:171], v[192:195], v[110:113]
	v_mfma_f32_16x16x32_bf16 v[102:105], v[176:179], v[192:195], v[102:105]
	v_mfma_f32_16x16x32_bf16 v[94:97], v[168:171], v[210:213], v[94:97]
	v_mfma_f32_16x16x32_bf16 v[86:89], v[176:179], v[210:213], v[86:89]
	v_mfma_f32_16x16x32_bf16 v[78:81], v[168:171], v[218:221], v[78:81]
	v_mfma_f32_16x16x32_bf16 v[70:73], v[176:179], v[218:221], v[70:73]
	s_barrier
	s_add_u32 s24, s24, 0x80080
	s_addc_u32 s25, s25, 0
	s_add_u32 s52, s52, 0xfff80080
	s_addc_u32 s53, s53, -1
	s_add_i32 s2, s2, s35
	s_mov_b32 m0, s2
	ds_read_b128 v[180:183], v155 offset:49152
	ds_read_b128 v[184:187], v155 offset:50176
	ds_read_b128 v[188:191], v155 offset:51200
	ds_read_b128 v[192:195], v155 offset:52224
	ds_read_b128 v[206:209], v155 offset:53248
	ds_read_b128 v[210:213], v155 offset:54272
	ds_read_b128 v[214:217], v155 offset:55296
	ds_read_b128 v[218:221], v155 offset:56320
	global_load_lds_dwordx4 v0, s[52:53]
	s_add_i32 m0, s2, 0x2000
	s_add_i32 s2, s50, s35
	global_load_lds_dwordx4 v130, s[52:53]
	s_mov_b32 m0, s2
	s_nop 0
	global_load_lds_dwordx4 v0, s[24:25]
	s_add_i32 m0, s2, 0x2000
	s_nop 0
	global_load_lds_dwordx4 v130, s[24:25]
	s_waitcnt vmcnt(6)
	s_waitcnt lgkmcnt(0)
	s_barrier
	s_waitcnt lgkmcnt(0)
	v_mfma_f32_16x16x32_bf16 v[58:61], v[140:143], v[180:183], v[58:61]
	v_mfma_f32_16x16x32_bf16 v[50:53], v[156:159], v[180:183], v[50:53]
	v_mfma_f32_16x16x32_bf16 v[42:45], v[140:143], v[188:191], v[42:45]
	v_mfma_f32_16x16x32_bf16 v[34:37], v[156:159], v[188:191], v[34:37]
	v_mfma_f32_16x16x32_bf16 v[26:29], v[140:143], v[206:209], v[26:29]
	v_mfma_f32_16x16x32_bf16 v[18:21], v[156:159], v[206:209], v[18:21]
	v_mfma_f32_16x16x32_bf16 v[10:13], v[140:143], v[214:217], v[10:13]
	v_mfma_f32_16x16x32_bf16 v[6:9], v[156:159], v[214:217], v[6:9]
	v_mfma_f32_16x16x32_bf16 v[58:61], v[148:151], v[184:187], v[58:61]
	v_mfma_f32_16x16x32_bf16 v[50:53], v[160:163], v[184:187], v[50:53]
	v_mfma_f32_16x16x32_bf16 v[42:45], v[148:151], v[192:195], v[42:45]
	v_mfma_f32_16x16x32_bf16 v[34:37], v[160:163], v[192:195], v[34:37]
	v_mfma_f32_16x16x32_bf16 v[26:29], v[148:151], v[210:213], v[26:29]
	v_mfma_f32_16x16x32_bf16 v[18:21], v[160:163], v[210:213], v[18:21]
	v_mfma_f32_16x16x32_bf16 v[10:13], v[148:151], v[218:221], v[10:13]
	v_mfma_f32_16x16x32_bf16 v[6:9], v[160:163], v[218:221], v[6:9]
	v_mfma_f32_16x16x32_bf16 v[62:65], v[164:167], v[180:183], v[62:65]
	v_mfma_f32_16x16x32_bf16 v[54:57], v[172:175], v[180:183], v[54:57]
	v_mfma_f32_16x16x32_bf16 v[46:49], v[164:167], v[188:191], v[46:49]
	v_mfma_f32_16x16x32_bf16 v[38:41], v[172:175], v[188:191], v[38:41]
	v_mfma_f32_16x16x32_bf16 v[30:33], v[164:167], v[206:209], v[30:33]
	v_mfma_f32_16x16x32_bf16 v[22:25], v[172:175], v[206:209], v[22:25]
	v_mfma_f32_16x16x32_bf16 v[14:17], v[164:167], v[214:217], v[14:17]
	v_mfma_f32_16x16x32_bf16 v[2:5], v[172:175], v[214:217], v[2:5]
	v_mfma_f32_16x16x32_bf16 v[62:65], v[168:171], v[184:187], v[62:65]
	v_mfma_f32_16x16x32_bf16 v[54:57], v[176:179], v[184:187], v[54:57]
	v_mfma_f32_16x16x32_bf16 v[46:49], v[168:171], v[192:195], v[46:49]
	v_mfma_f32_16x16x32_bf16 v[38:41], v[176:179], v[192:195], v[38:41]
	v_mfma_f32_16x16x32_bf16 v[30:33], v[168:171], v[210:213], v[30:33]
	v_mfma_f32_16x16x32_bf16 v[22:25], v[176:179], v[210:213], v[22:25]
	v_mfma_f32_16x16x32_bf16 v[14:17], v[168:171], v[218:221], v[14:17]
	v_mfma_f32_16x16x32_bf16 v[2:5], v[176:179], v[218:221], v[2:5]
	s_barrier
	s_add_i32 s49, s49, 2
	s_add_u32 s26, s26, 0x100
	s_addc_u32 s27, s27, 0
	s_add_u32 s46, s46, 0x100
	s_addc_u32 s47, s47, 0
	s_cmp_gt_u32 s49, 29
	s_cbranch_scc0 .LBB0_168
	s_nop 0
	s_and_b64 vcc, exec, s[14:15]
	s_cbranch_vccz .LBB0_171
	s_barrier

.LBB0_281:
	s_add_u32 s20, s18, 0x100
	s_addc_u32 s21, s19, 0
	s_add_i32 s2, 0, 0x10000
	s_cmpk_eq_i32 s42, 0x52
	s_cselect_b32 s25, s11, s21
	s_cselect_b32 s24, s10, s20
	s_cselect_b32 s23, s17, s41
	s_cselect_b32 s22, s16, s40
	s_add_u32 s100, s18, 0xffea8000
	s_addc_u32 s101, s19, -1
	s_add_i32 s43, 0, 0x14000
	v_add_u32_e32 v142, s2, v226
	v_add_u32_e32 v160, s43, v226
	ds_read_b128 v[126:129], v142
	ds_read_b128 v[134:137], v142 offset:1024
	ds_read_b128 v[138:141], v142 offset:2048
	ds_read_b128 v[142:145], v142 offset:3072
	ds_read_b128 v[148:151], v160
	ds_read_b128 v[152:155], v160 offset:1024
	ds_read_b128 v[156:159], v160 offset:2048
	ds_read_b128 v[160:163], v160 offset:3072
	s_add_i32 m0, s26, 0xc000
	ds_read_b128 v[164:167], v228
	ds_read_b128 v[168:171], v228 offset:1024
	ds_read_b128 v[172:175], v228 offset:2048
	ds_read_b128 v[176:179], v228 offset:3072
	ds_read_b128 v[180:183], v228 offset:4096
	ds_read_b128 v[184:187], v228 offset:5120
	ds_read_b128 v[208:211], v228 offset:6144
	ds_read_b128 v[212:215], v228 offset:7168
	s_mov_b32 m0, s36
	s_nop 0
	global_load_lds_dwordx4 v194, s[100:101]
	s_mov_b32 m0, s37
	s_nop 0
	global_load_lds_dwordx4 v206, s[100:101]
	s_add_i32 m0, s26, 0xc000
	s_nop 0
	global_load_lds_dwordx4 v194, s[18:19]
	s_add_i32 m0, s26, 0xe000
	s_nop 0
	global_load_lds_dwordx4 v206, s[18:19]
	s_waitcnt vmcnt(8)
	s_waitcnt lgkmcnt(0)
	s_barrier
	s_waitcnt lgkmcnt(0)
	v_mfma_f32_16x16x32_bf16 v[130:133], v[126:129], v[164:167], v[130:133]
	v_mfma_f32_16x16x32_bf16 v[122:125], v[138:141], v[164:167], v[122:125]
	v_mfma_f32_16x16x32_bf16 v[110:113], v[126:129], v[172:175], v[110:113]
	v_mfma_f32_16x16x32_bf16 v[106:109], v[138:141], v[172:175], v[106:109]
	v_mfma_f32_16x16x32_bf16 v[94:97], v[126:129], v[180:183], v[94:97]
	v_mfma_f32_16x16x32_bf16 v[90:93], v[138:141], v[180:183], v[90:93]
	v_mfma_f32_16x16x32_bf16 v[78:81], v[126:129], v[208:211], v[78:81]
	v_mfma_f32_16x16x32_bf16 v[74:77], v[138:141], v[208:211], v[74:77]
	v_mfma_f32_16x16x32_bf16 v[130:133], v[134:137], v[168:171], v[130:133]
	v_mfma_f32_16x16x32_bf16 v[122:125], v[142:145], v[168:171], v[122:125]
	v_mfma_f32_16x16x32_bf16 v[110:113], v[134:137], v[176:179], v[110:113]
	v_mfma_f32_16x16x32_bf16 v[106:109], v[142:145], v[176:179], v[106:109]
	v_mfma_f32_16x16x32_bf16 v[94:97], v[134:137], v[184:187], v[94:97]
	v_mfma_f32_16x16x32_bf16 v[90:93], v[142:145], v[184:187], v[90:93]
	v_mfma_f32_16x16x32_bf16 v[78:81], v[134:137], v[212:215], v[78:81]
	v_mfma_f32_16x16x32_bf16 v[74:77], v[142:145], v[212:215], v[74:77]
	v_mfma_f32_16x16x32_bf16 v[118:121], v[148:151], v[164:167], v[118:121]
	v_mfma_f32_16x16x32_bf16 v[114:117], v[156:159], v[164:167], v[114:117]
	v_mfma_f32_16x16x32_bf16 v[102:105], v[148:151], v[172:175], v[102:105]
	v_mfma_f32_16x16x32_bf16 v[98:101], v[156:159], v[172:175], v[98:101]
	v_mfma_f32_16x16x32_bf16 v[86:89], v[148:151], v[180:183], v[86:89]
	v_mfma_f32_16x16x32_bf16 v[82:85], v[156:159], v[180:183], v[82:85]
	v_mfma_f32_16x16x32_bf16 v[70:73], v[148:151], v[208:211], v[70:73]
	v_mfma_f32_16x16x32_bf16 v[66:69], v[156:159], v[208:211], v[66:69]
	v_mfma_f32_16x16x32_bf16 v[118:121], v[152:155], v[168:171], v[118:121]
	v_mfma_f32_16x16x32_bf16 v[114:117], v[160:163], v[168:171], v[114:117]
	v_mfma_f32_16x16x32_bf16 v[102:105], v[152:155], v[176:179], v[102:105]
	v_mfma_f32_16x16x32_bf16 v[98:101], v[160:163], v[176:179], v[98:101]
	v_mfma_f32_16x16x32_bf16 v[86:89], v[152:155], v[184:187], v[86:89]
	v_mfma_f32_16x16x32_bf16 v[82:85], v[160:163], v[184:187], v[82:85]
	v_mfma_f32_16x16x32_bf16 v[70:73], v[152:155], v[212:215], v[70:73]
	v_mfma_f32_16x16x32_bf16 v[66:69], v[160:163], v[212:215], v[66:69]
	s_barrier
	s_add_u32 s18, s22, 0x158000
	s_addc_u32 s19, s23, 0
	s_add_i32 s2, s2, s1
	s_mov_b32 m0, s2
	ds_read_b128 v[164:167], v228 offset:16384
	ds_read_b128 v[168:171], v228 offset:17408
	ds_read_b128 v[172:175], v228 offset:18432
	ds_read_b128 v[176:179], v228 offset:19456
	ds_read_b128 v[180:183], v228 offset:20480
	ds_read_b128 v[184:187], v228 offset:21504
	ds_read_b128 v[208:211], v228 offset:22528
	ds_read_b128 v[212:215], v228 offset:23552
	global_load_lds_dwordx4 v0, s[22:23]
	s_add_i32 m0, s2, 0x2000
	s_add_i32 s2, s43, s1
	global_load_lds_dwordx4 v188, s[22:23]
	s_mov_b32 m0, s2
	s_nop 0
	global_load_lds_dwordx4 v0, s[18:19]
	s_add_i32 m0, s2, 0x2000
	s_nop 0
	global_load_lds_dwordx4 v188, s[18:19]
	s_waitcnt vmcnt(6)
	s_waitcnt lgkmcnt(0)
	s_barrier
	s_waitcnt lgkmcnt(0)
	v_mfma_f32_16x16x32_bf16 v[62:65], v[126:129], v[164:167], v[62:65]
	v_mfma_f32_16x16x32_bf16 v[58:61], v[138:141], v[164:167], v[58:61]
	v_mfma_f32_16x16x32_bf16 v[46:49], v[126:129], v[172:175], v[46:49]
	v_mfma_f32_16x16x32_bf16 v[42:45], v[138:141], v[172:175], v[42:45]
	v_mfma_f32_16x16x32_bf16 v[30:33], v[126:129], v[180:183], v[30:33]
	v_mfma_f32_16x16x32_bf16 v[26:29], v[138:141], v[180:183], v[26:29]
	v_mfma_f32_16x16x32_bf16 v[14:17], v[126:129], v[208:211], v[14:17]
	v_mfma_f32_16x16x32_bf16 v[10:13], v[138:141], v[208:211], v[10:13]
	v_mfma_f32_16x16x32_bf16 v[62:65], v[134:137], v[168:171], v[62:65]
	v_mfma_f32_16x16x32_bf16 v[58:61], v[142:145], v[168:171], v[58:61]
	v_mfma_f32_16x16x32_bf16 v[46:49], v[134:137], v[176:179], v[46:49]
	v_mfma_f32_16x16x32_bf16 v[42:45], v[142:145], v[176:179], v[42:45]
	v_mfma_f32_16x16x32_bf16 v[30:33], v[134:137], v[184:187], v[30:33]
	v_mfma_f32_16x16x32_bf16 v[26:29], v[142:145], v[184:187], v[26:29]
	v_mfma_f32_16x16x32_bf16 v[14:17], v[134:137], v[212:215], v[14:17]
	v_mfma_f32_16x16x32_bf16 v[10:13], v[142:145], v[212:215], v[10:13]
	v_mfma_f32_16x16x32_bf16 v[54:57], v[148:151], v[164:167], v[54:57]
	v_mfma_f32_16x16x32_bf16 v[50:53], v[156:159], v[164:167], v[50:53]
	v_mfma_f32_16x16x32_bf16 v[38:41], v[148:151], v[172:175], v[38:41]
	v_mfma_f32_16x16x32_bf16 v[34:37], v[156:159], v[172:175], v[34:37]
	v_mfma_f32_16x16x32_bf16 v[22:25], v[148:151], v[180:183], v[22:25]
	v_mfma_f32_16x16x32_bf16 v[18:21], v[156:159], v[180:183], v[18:21]
	v_mfma_f32_16x16x32_bf16 v[6:9], v[148:151], v[208:211], v[6:9]
	v_mfma_f32_16x16x32_bf16 v[2:5], v[156:159], v[208:211], v[2:5]
	v_mfma_f32_16x16x32_bf16 v[54:57], v[152:155], v[168:171], v[54:57]
	v_mfma_f32_16x16x32_bf16 v[50:53], v[160:163], v[168:171], v[50:53]
	v_mfma_f32_16x16x32_bf16 v[38:41], v[152:155], v[176:179], v[38:41]
	v_mfma_f32_16x16x32_bf16 v[34:37], v[160:163], v[176:179], v[34:37]
	v_mfma_f32_16x16x32_bf16 v[22:25], v[152:155], v[184:187], v[22:25]
	v_mfma_f32_16x16x32_bf16 v[18:21], v[160:163], v[184:187], v[18:21]
	v_mfma_f32_16x16x32_bf16 v[6:9], v[152:155], v[212:215], v[6:9]
	v_mfma_f32_16x16x32_bf16 v[2:5], v[160:163], v[212:215], v[2:5]
	s_barrier
	s_add_u32 s18, s24, 0x158000
	s_addc_u32 s19, s25, 0
	s_add_i32 s2, 0, 0x18000
	s_add_i32 s43, 0, 0x1c000
	v_add_u32_e32 v142, s2, v226
	v_add_u32_e32 v160, s43, v226
	ds_read_b128 v[126:129], v142
	ds_read_b128 v[134:137], v142 offset:1024
	ds_read_b128 v[138:141], v142 offset:2048
	ds_read_b128 v[142:145], v142 offset:3072
	ds_read_b128 v[148:151], v160
	ds_read_b128 v[152:155], v160 offset:1024
	ds_read_b128 v[156:159], v160 offset:2048
	ds_read_b128 v[160:163], v160 offset:3072
	s_mov_b32 m0, s30
	ds_read_b128 v[164:167], v228 offset:32768
	ds_read_b128 v[168:171], v228 offset:33792
	ds_read_b128 v[172:175], v228 offset:34816
	ds_read_b128 v[176:179], v228 offset:35840
	ds_read_b128 v[180:183], v228 offset:36864
	ds_read_b128 v[184:187], v228 offset:37888
	ds_read_b128 v[208:211], v228 offset:38912
	ds_read_b128 v[212:215], v228 offset:39936
	s_mov_b32 m0, s26
	s_nop 0
	global_load_lds_dwordx4 v192, s[24:25]
	s_mov_b32 m0, s27
	s_nop 0
	global_load_lds_dwordx4 v190, s[24:25]
	s_mov_b32 m0, s30
	s_nop 0
	global_load_lds_dwordx4 v192, s[18:19]
	s_mov_b32 m0, s31
	s_nop 0
	global_load_lds_dwordx4 v190, s[18:19]
	s_waitcnt vmcnt(8)
	s_waitcnt lgkmcnt(0)
	s_barrier
	s_waitcnt lgkmcnt(0)
	v_mfma_f32_16x16x32_bf16 v[130:133], v[126:129], v[164:167], v[130:133]
	v_mfma_f32_16x16x32_bf16 v[122:125], v[138:141], v[164:167], v[122:125]
	v_mfma_f32_16x16x32_bf16 v[110:113], v[126:129], v[172:175], v[110:113]
	v_mfma_f32_16x16x32_bf16 v[106:109], v[138:141], v[172:175], v[106:109]
	v_mfma_f32_16x16x32_bf16 v[94:97], v[126:129], v[180:183], v[94:97]
	v_mfma_f32_16x16x32_bf16 v[90:93], v[138:141], v[180:183], v[90:93]
	v_mfma_f32_16x16x32_bf16 v[78:81], v[126:129], v[208:211], v[78:81]
	v_mfma_f32_16x16x32_bf16 v[74:77], v[138:141], v[208:211], v[74:77]
	v_mfma_f32_16x16x32_bf16 v[130:133], v[134:137], v[168:171], v[130:133]
	v_mfma_f32_16x16x32_bf16 v[122:125], v[142:145], v[168:171], v[122:125]
	v_mfma_f32_16x16x32_bf16 v[110:113], v[134:137], v[176:179], v[110:113]
	v_mfma_f32_16x16x32_bf16 v[106:109], v[142:145], v[176:179], v[106:109]
	v_mfma_f32_16x16x32_bf16 v[94:97], v[134:137], v[184:187], v[94:97]
	v_mfma_f32_16x16x32_bf16 v[90:93], v[142:145], v[184:187], v[90:93]
	v_mfma_f32_16x16x32_bf16 v[78:81], v[134:137], v[212:215], v[78:81]
	v_mfma_f32_16x16x32_bf16 v[74:77], v[142:145], v[212:215], v[74:77]
	v_mfma_f32_16x16x32_bf16 v[118:121], v[148:151], v[164:167], v[118:121]
	v_mfma_f32_16x16x32_bf16 v[114:117], v[156:159], v[164:167], v[114:117]
	v_mfma_f32_16x16x32_bf16 v[102:105], v[148:151], v[172:175], v[102:105]
	v_mfma_f32_16x16x32_bf16 v[98:101], v[156:159], v[172:175], v[98:101]
	v_mfma_f32_16x16x32_bf16 v[86:89], v[148:151], v[180:183], v[86:89]
	v_mfma_f32_16x16x32_bf16 v[82:85], v[156:159], v[180:183], v[82:85]
	v_mfma_f32_16x16x32_bf16 v[70:73], v[148:151], v[208:211], v[70:73]
	v_mfma_f32_16x16x32_bf16 v[66:69], v[156:159], v[208:211], v[66:69]
	v_mfma_f32_16x16x32_bf16 v[118:121], v[152:155], v[168:171], v[118:121]
	v_mfma_f32_16x16x32_bf16 v[114:117], v[160:163], v[168:171], v[114:117]
	v_mfma_f32_16x16x32_bf16 v[102:105], v[152:155], v[176:179], v[102:105]
	v_mfma_f32_16x16x32_bf16 v[98:101], v[160:163], v[176:179], v[98:101]
	v_mfma_f32_16x16x32_bf16 v[86:89], v[152:155], v[184:187], v[86:89]
	v_mfma_f32_16x16x32_bf16 v[82:85], v[160:163], v[184:187], v[82:85]
	v_mfma_f32_16x16x32_bf16 v[70:73], v[152:155], v[212:215], v[70:73]
	v_mfma_f32_16x16x32_bf16 v[66:69], v[160:163], v[212:215], v[66:69]
	s_barrier
	s_add_u32 s18, s22, 0x158080
	s_addc_u32 s19, s23, 0
	s_add_u32 s22, s22, 0x80
	s_addc_u32 s23, s23, 0
	s_add_i32 s2, s2, s1
	s_mov_b32 m0, s2
	ds_read_b128 v[164:167], v228 offset:49152
	ds_read_b128 v[168:171], v228 offset:50176
	ds_read_b128 v[172:175], v228 offset:51200
	ds_read_b128 v[176:179], v228 offset:52224
	ds_read_b128 v[180:183], v228 offset:53248
	ds_read_b128 v[184:187], v228 offset:54272
	ds_read_b128 v[208:211], v228 offset:55296
	ds_read_b128 v[212:215], v228 offset:56320
	global_load_lds_dwordx4 v0, s[22:23]
	s_add_i32 m0, s2, 0x2000
	s_add_i32 s2, s43, s1
	global_load_lds_dwordx4 v188, s[22:23]
	s_mov_b32 m0, s2
	s_nop 0
	global_load_lds_dwordx4 v0, s[18:19]
	s_add_i32 m0, s2, 0x2000
	s_nop 0
	global_load_lds_dwordx4 v188, s[18:19]
	s_waitcnt vmcnt(6)
	s_waitcnt lgkmcnt(0)
	s_barrier
	s_waitcnt lgkmcnt(0)
	v_mfma_f32_16x16x32_bf16 v[62:65], v[126:129], v[164:167], v[62:65]
	v_mfma_f32_16x16x32_bf16 v[58:61], v[138:141], v[164:167], v[58:61]
	v_mfma_f32_16x16x32_bf16 v[46:49], v[126:129], v[172:175], v[46:49]
	v_mfma_f32_16x16x32_bf16 v[42:45], v[138:141], v[172:175], v[42:45]
	v_mfma_f32_16x16x32_bf16 v[30:33], v[126:129], v[180:183], v[30:33]
	v_mfma_f32_16x16x32_bf16 v[26:29], v[138:141], v[180:183], v[26:29]
	v_mfma_f32_16x16x32_bf16 v[14:17], v[126:129], v[208:211], v[14:17]
	v_mfma_f32_16x16x32_bf16 v[10:13], v[138:141], v[208:211], v[10:13]
	v_mfma_f32_16x16x32_bf16 v[62:65], v[134:137], v[168:171], v[62:65]
	v_mfma_f32_16x16x32_bf16 v[58:61], v[142:145], v[168:171], v[58:61]
	v_mfma_f32_16x16x32_bf16 v[46:49], v[134:137], v[176:179], v[46:49]
	v_mfma_f32_16x16x32_bf16 v[42:45], v[142:145], v[176:179], v[42:45]
	v_mfma_f32_16x16x32_bf16 v[30:33], v[134:137], v[184:187], v[30:33]
	v_mfma_f32_16x16x32_bf16 v[26:29], v[142:145], v[184:187], v[26:29]
	v_mfma_f32_16x16x32_bf16 v[14:17], v[134:137], v[212:215], v[14:17]
	v_mfma_f32_16x16x32_bf16 v[10:13], v[142:145], v[212:215], v[10:13]
	v_mfma_f32_16x16x32_bf16 v[54:57], v[148:151], v[164:167], v[54:57]
	v_mfma_f32_16x16x32_bf16 v[50:53], v[156:159], v[164:167], v[50:53]
	v_mfma_f32_16x16x32_bf16 v[38:41], v[148:151], v[172:175], v[38:41]
	v_mfma_f32_16x16x32_bf16 v[34:37], v[156:159], v[172:175], v[34:37]
	v_mfma_f32_16x16x32_bf16 v[22:25], v[148:151], v[180:183], v[22:25]
	v_mfma_f32_16x16x32_bf16 v[18:21], v[156:159], v[180:183], v[18:21]
	v_mfma_f32_16x16x32_bf16 v[6:9], v[148:151], v[208:211], v[6:9]
	v_mfma_f32_16x16x32_bf16 v[2:5], v[156:159], v[208:211], v[2:5]
	v_mfma_f32_16x16x32_bf16 v[54:57], v[152:155], v[168:171], v[54:57]
	v_mfma_f32_16x16x32_bf16 v[50:53], v[160:163], v[168:171], v[50:53]
	v_mfma_f32_16x16x32_bf16 v[38:41], v[152:155], v[176:179], v[38:41]
	v_mfma_f32_16x16x32_bf16 v[34:37], v[160:163], v[176:179], v[34:37]
	v_mfma_f32_16x16x32_bf16 v[22:25], v[152:155], v[184:187], v[22:25]
	v_mfma_f32_16x16x32_bf16 v[18:21], v[160:163], v[184:187], v[18:21]
	v_mfma_f32_16x16x32_bf16 v[6:9], v[152:155], v[212:215], v[6:9]
	v_mfma_f32_16x16x32_bf16 v[2:5], v[160:163], v[212:215], v[2:5]
	s_barrier
	s_add_i32 s42, s42, 2
	s_add_u32 s40, s40, 0x100
	s_addc_u32 s41, s41, 0
	s_cmpk_gt_u32 s42, 0x53
	s_mov_b64 s[18:19], s[20:21]
	s_cbranch_scc0 .LBB0_281
	s_nop 0
	s_nop 0
	s_nop 0
	s_nop 0
	v_lshl_or_b32 v210, s3, 8, v227
	v_lshl_add_u32 v224, s34, 8, v147
	v_ashrrev_i32_e32 v211, 31, v210
	v_lshlrev_b64 v[126:127], 1, v[210:211]
	v_ashrrev_i32_e32 v225, 31, v224
	v_lshl_add_u64 v[128:129], s[12:13], 0, v[126:127]
	v_lshlrev_b64 v[134:135], 12, v[224:225]
	v_lshl_add_u64 v[136:137], v[128:129], 0, v[134:135]
	global_load_dwordx4 v[240:243], v[136:137], off
	global_load_dwordx4 v[244:247], v[136:137], off offset:256
	v_or_b32_e32 v222, 16, v224
	v_or_b32_e32 v220, 32, v224
	v_or_b32_e32 v218, 48, v224
	v_add_u32_e32 v216, 0x80, v224
	v_add_u32_e32 v214, 0x90, v224
	v_add_u32_e32 v212, 0xa0, v224
	v_add_u32_e32 v208, 0xb0, v224
	v_ashrrev_i32_e32 v223, 31, v222
	v_ashrrev_i32_e32 v221, 31, v220
	v_ashrrev_i32_e32 v219, 31, v218
	v_ashrrev_i32_e32 v217, 31, v216
	v_ashrrev_i32_e32 v215, 31, v214
	v_ashrrev_i32_e32 v213, 31, v212
	v_ashrrev_i32_e32 v209, 31, v208
	v_lshlrev_b64 v[136:137], 12, v[222:223]
	v_lshlrev_b64 v[138:139], 12, v[220:221]
	v_lshlrev_b64 v[140:141], 12, v[218:219]
	v_lshlrev_b64 v[142:143], 12, v[216:217]
	v_lshlrev_b64 v[144:145], 12, v[214:215]
	v_lshlrev_b64 v[148:149], 12, v[212:213]
	v_lshlrev_b64 v[150:151], 12, v[208:209]
	v_lshl_add_u64 v[134:135], s[12:13], 0, v[134:135]
	v_lshl_add_u64 v[136:137], v[128:129], 0, v[136:137]
	v_lshl_add_u64 v[138:139], v[128:129], 0, v[138:139]
	v_lshl_add_u64 v[140:141], v[128:129], 0, v[140:141]
	v_lshl_add_u64 v[142:143], v[128:129], 0, v[142:143]
	v_lshl_add_u64 v[144:145], v[128:129], 0, v[144:145]
	v_lshl_add_u64 v[248:249], v[128:129], 0, v[148:149]
	v_lshl_add_u64 v[128:129], v[128:129], 0, v[150:151]
	v_lshl_add_u64 v[250:251], v[134:135], 0, v[126:127]
	global_load_dwordx4 v[184:187], v[136:137], off
	global_load_dwordx4 v[180:183], v[136:137], off offset:256
	global_load_dwordx4 v[176:179], v[138:139], off
	global_load_dwordx4 v[172:175], v[138:139], off offset:256
	global_load_dwordx4 v[168:171], v[140:141], off
	global_load_dwordx4 v[164:167], v[140:141], off offset:256
	global_load_dwordx4 v[160:163], v[142:143], off
	global_load_dwordx4 v[156:159], v[142:143], off offset:256
	global_load_dwordx4 v[152:155], v[144:145], off
	global_load_dwordx4 v[148:151], v[144:145], off offset:256
	s_nop 0
	global_load_dwordx4 v[142:145], v[248:249], off
	global_load_dwordx4 v[138:141], v[248:249], off offset:256
	global_load_dwordx4 v[134:137], v[128:129], off
	s_nop 0
	global_load_dwordx4 v[126:129], v[128:129], off offset:256
	s_lshl_b32 s18, s3, 2
	s_ashr_i32 s19, s18, 31
	s_waitcnt vmcnt(0)
	v_lshlrev_b32_e32 v248, 16, v240
	v_and_b32_e32 v249, 0xffff0000, v240
	v_lshlrev_b32_e32 v240, 16, v241
	v_and_b32_e32 v241, 0xffff0000, v241
	v_lshlrev_b32_e32 v252, 16, v242
	v_and_b32_e32 v253, 0xffff0000, v242
	v_lshlrev_b32_e32 v242, 16, v243
	v_and_b32_e32 v243, 0xffff0000, v243
	v_pk_fma_f32 v[132:133], v[132:133], 0.5, v[240:241] op_sel_hi:[1,0,1]
	v_pk_fma_f32 v[240:241], v[124:125], 0.5, v[242:243] op_sel_hi:[1,0,1]
	v_pk_fma_f32 v[124:125], v[122:123], 0.5, v[252:253] op_sel_hi:[1,0,1]
	v_pk_fma_f32 v[130:131], v[130:131], 0.5, v[248:249] op_sel_hi:[1,0,1]
	v_lshlrev_b32_e32 v236, 16, v244
	v_cvt_pk_bf16_f32 v122, v130, v131
	v_cvt_pk_bf16_f32 v123, v132, v133
	v_cvt_pk_bf16_f32 v124, v124, v125
	v_cvt_pk_bf16_f32 v125, v240, v241
	global_store_dwordx4 v[250:251], v[122:125], off
	v_lshlrev_b32_e32 v130, 16, v122
	v_lshlrev_b32_e32 v131, 16, v123
	v_and_b32_e32 v122, 0xffff0000, v122
	v_and_b32_e32 v123, 0xffff0000, v123
	v_lshlrev_b32_e32 v132, 16, v124
	v_and_b32_e32 v124, 0xffff0000, v124
	v_lshlrev_b32_e32 v133, 16, v125
	v_and_b32_e32 v125, 0xffff0000, v125
	v_mul_f32_e32 v122, v122, v122
	v_mul_f32_e32 v123, v123, v123
	v_mul_f32_e32 v124, v124, v124
	v_mul_f32_e32 v125, v125, v125
	v_fmac_f32_e32 v122, v130, v130
	v_fmac_f32_e32 v123, v131, v131
	v_fmac_f32_e32 v124, v132, v132
	v_fmac_f32_e32 v125, v133, v133
	v_add_f32_e32 v122, v122, v123
	v_add_f32_e32 v123, v124, v125
	v_and_b32_e32 v237, 0xffff0000, v244
	v_add_f32_e32 v132, v122, v123
	v_lshlrev_b32_e32 v122, 16, v245
	v_and_b32_e32 v123, 0xffff0000, v245
	v_lshlrev_b32_e32 v124, 16, v246
	v_and_b32_e32 v125, 0xffff0000, v246
	v_lshlrev_b32_e32 v130, 16, v247
	v_and_b32_e32 v131, 0xffff0000, v247
	v_pk_fma_f32 v[120:121], v[120:121], 0.5, v[122:123] op_sel_hi:[1,0,1]
	v_pk_fma_f32 v[118:119], v[118:119], 0.5, v[236:237] op_sel_hi:[1,0,1]
	v_pk_fma_f32 v[122:123], v[116:117], 0.5, v[130:131] op_sel_hi:[1,0,1]
	v_pk_fma_f32 v[116:117], v[114:115], 0.5, v[124:125] op_sel_hi:[1,0,1]
	v_cvt_pk_bf16_f32 v114, v118, v119
	v_cvt_pk_bf16_f32 v115, v120, v121
	s_nop 0
	v_cvt_pk_bf16_f32 v116, v116, v117
	v_cvt_pk_bf16_f32 v117, v122, v123
	global_store_dwordx4 v[250:251], v[114:117], off offset:256
	v_lshlrev_b32_e32 v118, 16, v114
	v_lshlrev_b32_e32 v119, 16, v115
	v_and_b32_e32 v114, 0xffff0000, v114
	v_and_b32_e32 v115, 0xffff0000, v115
	v_mul_f32_e32 v114, v114, v114
	v_mul_f32_e32 v115, v115, v115
	v_lshlrev_b32_e32 v120, 16, v116
	v_and_b32_e32 v116, 0xffff0000, v116
	v_lshlrev_b32_e32 v121, 16, v117
	v_and_b32_e32 v117, 0xffff0000, v117
	v_fmac_f32_e32 v114, v118, v118
	v_fmac_f32_e32 v115, v119, v119
	v_add_f32_e32 v114, v114, v115
	v_mul_f32_e32 v115, v116, v116
	v_mul_f32_e32 v116, v117, v117
	v_fmac_f32_e32 v115, v120, v120
	v_fmac_f32_e32 v116, v121, v121
	v_add_f32_e32 v115, v115, v116
	v_add_f32_e32 v114, v114, v115
	s_mov_b32 s2, 0
	v_add_f32_e32 v114, v132, v114
	v_mbcnt_lo_u32_b32 v115, -1, s2
	v_mbcnt_hi_u32_b32 v115, -1, v115
	v_lshlrev_b32_e32 v115, 2, v115
	v_xor_b32_e32 v115, 64, v115
	ds_bpermute_b32 v115, v115, v114
	s_mov_b32 s2, 0
	s_waitcnt lgkmcnt(0)
	v_add_f32_e32 v114, v114, v115
	v_mbcnt_lo_u32_b32 v115, -1, s2
	v_mbcnt_hi_u32_b32 v115, -1, v115
	v_lshlrev_b32_e32 v115, 2, v115
	v_xor_b32_e32 v115, 0x80, v115
	ds_bpermute_b32 v115, v115, v114
	s_and_saveexec_b64 s[20:21], s[6:7]
	s_cbranch_execz .LBB0_284
	v_lshlrev_b64 v[116:117], 7, v[224:225]
	v_lshl_add_u64 v[116:117], s[14:15], 0, v[116:117]
	v_lshl_add_u64 v[116:117], s[18:19], 2, v[116:117]
	s_lshl_b32 s50, s35, 2
	v_lshl_add_u64 v[116:117], v[116:117], 0, s[50:51]
	s_waitcnt lgkmcnt(0)
	v_add_f32_e32 v114, v114, v115
	global_store_dword v[116:117], v114, off

.LBB0_322:
	s_add_u32 s22, s20, 0x100
	s_addc_u32 s23, s21, 0
	s_add_i32 s2, 0, 0x10000
	s_cmpk_eq_i32 s42, 0x52
	s_cselect_b32 s27, s9, s23
	s_cselect_b32 s26, s8, s22
	s_cselect_b32 s25, s19, s41
	s_cselect_b32 s24, s18, s40
	s_add_u32 s100, s20, 0xffea8000
	s_addc_u32 s101, s21, -1
	s_add_i32 s43, 0, 0x14000
	v_add_u32_e32 v142, s2, v240
	v_add_u32_e32 v160, s43, v240
	ds_read_b128 v[130:133], v142
	ds_read_b128 v[134:137], v142 offset:1024
	ds_read_b128 v[138:141], v142 offset:2048
	ds_read_b128 v[142:145], v142 offset:3072
	ds_read_b128 v[148:151], v160
	ds_read_b128 v[152:155], v160 offset:1024
	ds_read_b128 v[156:159], v160 offset:2048
	ds_read_b128 v[160:163], v160 offset:3072
	s_add_i32 m0, s1, 0xc000
	ds_read_b128 v[164:167], v242
	ds_read_b128 v[168:171], v242 offset:1024
	ds_read_b128 v[172:175], v242 offset:2048
	ds_read_b128 v[176:179], v242 offset:3072
	ds_read_b128 v[180:183], v242 offset:4096
	ds_read_b128 v[184:187], v242 offset:5120
	ds_read_b128 v[188:191], v242 offset:6144
	ds_read_b128 v[212:215], v242 offset:7168
	s_mov_b32 m0, s35
	s_nop 0
	global_load_lds_dwordx4 v208, s[100:101]
	s_mov_b32 m0, s36
	s_nop 0
	global_load_lds_dwordx4 v210, s[100:101]
	s_add_i32 m0, s1, 0xc000
	s_nop 0
	global_load_lds_dwordx4 v208, s[20:21]
	s_add_i32 m0, s1, 0xe000
	s_nop 0
	global_load_lds_dwordx4 v210, s[20:21]
	s_waitcnt vmcnt(8)
	s_waitcnt lgkmcnt(0)
	s_barrier
	s_waitcnt lgkmcnt(0)
	v_mfma_f32_16x16x32_bf16 v[126:129], v[130:133], v[164:167], v[126:129]
	v_mfma_f32_16x16x32_bf16 v[122:125], v[138:141], v[164:167], v[122:125]
	v_mfma_f32_16x16x32_bf16 v[110:113], v[130:133], v[172:175], v[110:113]
	v_mfma_f32_16x16x32_bf16 v[106:109], v[138:141], v[172:175], v[106:109]
	v_mfma_f32_16x16x32_bf16 v[94:97], v[130:133], v[180:183], v[94:97]
	v_mfma_f32_16x16x32_bf16 v[90:93], v[138:141], v[180:183], v[90:93]
	v_mfma_f32_16x16x32_bf16 v[78:81], v[130:133], v[188:191], v[78:81]
	v_mfma_f32_16x16x32_bf16 v[74:77], v[138:141], v[188:191], v[74:77]
	v_mfma_f32_16x16x32_bf16 v[126:129], v[134:137], v[168:171], v[126:129]
	v_mfma_f32_16x16x32_bf16 v[122:125], v[142:145], v[168:171], v[122:125]
	v_mfma_f32_16x16x32_bf16 v[110:113], v[134:137], v[176:179], v[110:113]
	v_mfma_f32_16x16x32_bf16 v[106:109], v[142:145], v[176:179], v[106:109]
	v_mfma_f32_16x16x32_bf16 v[94:97], v[134:137], v[184:187], v[94:97]
	v_mfma_f32_16x16x32_bf16 v[90:93], v[142:145], v[184:187], v[90:93]
	v_mfma_f32_16x16x32_bf16 v[78:81], v[134:137], v[212:215], v[78:81]
	v_mfma_f32_16x16x32_bf16 v[74:77], v[142:145], v[212:215], v[74:77]
	v_mfma_f32_16x16x32_bf16 v[118:121], v[148:151], v[164:167], v[118:121]
	v_mfma_f32_16x16x32_bf16 v[114:117], v[156:159], v[164:167], v[114:117]
	v_mfma_f32_16x16x32_bf16 v[102:105], v[148:151], v[172:175], v[102:105]
	v_mfma_f32_16x16x32_bf16 v[98:101], v[156:159], v[172:175], v[98:101]
	v_mfma_f32_16x16x32_bf16 v[86:89], v[148:151], v[180:183], v[86:89]
	v_mfma_f32_16x16x32_bf16 v[82:85], v[156:159], v[180:183], v[82:85]
	v_mfma_f32_16x16x32_bf16 v[70:73], v[148:151], v[188:191], v[70:73]
	v_mfma_f32_16x16x32_bf16 v[66:69], v[156:159], v[188:191], v[66:69]
	v_mfma_f32_16x16x32_bf16 v[118:121], v[152:155], v[168:171], v[118:121]
	v_mfma_f32_16x16x32_bf16 v[114:117], v[160:163], v[168:171], v[114:117]
	v_mfma_f32_16x16x32_bf16 v[102:105], v[152:155], v[176:179], v[102:105]
	v_mfma_f32_16x16x32_bf16 v[98:101], v[160:163], v[176:179], v[98:101]
	v_mfma_f32_16x16x32_bf16 v[86:89], v[152:155], v[184:187], v[86:89]
	v_mfma_f32_16x16x32_bf16 v[82:85], v[160:163], v[184:187], v[82:85]
	v_mfma_f32_16x16x32_bf16 v[70:73], v[152:155], v[212:215], v[70:73]
	v_mfma_f32_16x16x32_bf16 v[66:69], v[160:163], v[212:215], v[66:69]
	s_barrier
	s_add_u32 s20, s24, 0x158000
	s_addc_u32 s21, s25, 0
	s_add_i32 s2, s2, s0
	s_mov_b32 m0, s2
	ds_read_b128 v[164:167], v242 offset:16384
	ds_read_b128 v[168:171], v242 offset:17408
	ds_read_b128 v[172:175], v242 offset:18432
	ds_read_b128 v[176:179], v242 offset:19456
	ds_read_b128 v[180:183], v242 offset:20480
	ds_read_b128 v[184:187], v242 offset:21504
	ds_read_b128 v[188:191], v242 offset:22528
	ds_read_b128 v[212:215], v242 offset:23552
	global_load_lds_dwordx4 v0, s[24:25]
	s_add_i32 m0, s2, 0x2000
	s_add_i32 s2, s43, s0
	global_load_lds_dwordx4 v192, s[24:25]
	s_mov_b32 m0, s2
	s_nop 0
	global_load_lds_dwordx4 v0, s[20:21]
	s_add_i32 m0, s2, 0x2000
	s_nop 0
	global_load_lds_dwordx4 v192, s[20:21]
	s_waitcnt vmcnt(6)
	s_waitcnt lgkmcnt(0)
	s_barrier
	s_waitcnt lgkmcnt(0)
	v_mfma_f32_16x16x32_bf16 v[62:65], v[130:133], v[164:167], v[62:65]
	v_mfma_f32_16x16x32_bf16 v[58:61], v[138:141], v[164:167], v[58:61]
	v_mfma_f32_16x16x32_bf16 v[46:49], v[130:133], v[172:175], v[46:49]
	v_mfma_f32_16x16x32_bf16 v[42:45], v[138:141], v[172:175], v[42:45]
	v_mfma_f32_16x16x32_bf16 v[30:33], v[130:133], v[180:183], v[30:33]
	v_mfma_f32_16x16x32_bf16 v[26:29], v[138:141], v[180:183], v[26:29]
	v_mfma_f32_16x16x32_bf16 v[14:17], v[130:133], v[188:191], v[14:17]
	v_mfma_f32_16x16x32_bf16 v[10:13], v[138:141], v[188:191], v[10:13]
	v_mfma_f32_16x16x32_bf16 v[62:65], v[134:137], v[168:171], v[62:65]
	v_mfma_f32_16x16x32_bf16 v[58:61], v[142:145], v[168:171], v[58:61]
	v_mfma_f32_16x16x32_bf16 v[46:49], v[134:137], v[176:179], v[46:49]
	v_mfma_f32_16x16x32_bf16 v[42:45], v[142:145], v[176:179], v[42:45]
	v_mfma_f32_16x16x32_bf16 v[30:33], v[134:137], v[184:187], v[30:33]
	v_mfma_f32_16x16x32_bf16 v[26:29], v[142:145], v[184:187], v[26:29]
	v_mfma_f32_16x16x32_bf16 v[14:17], v[134:137], v[212:215], v[14:17]
	v_mfma_f32_16x16x32_bf16 v[10:13], v[142:145], v[212:215], v[10:13]
	v_mfma_f32_16x16x32_bf16 v[54:57], v[148:151], v[164:167], v[54:57]
	v_mfma_f32_16x16x32_bf16 v[50:53], v[156:159], v[164:167], v[50:53]
	v_mfma_f32_16x16x32_bf16 v[38:41], v[148:151], v[172:175], v[38:41]
	v_mfma_f32_16x16x32_bf16 v[34:37], v[156:159], v[172:175], v[34:37]
	v_mfma_f32_16x16x32_bf16 v[22:25], v[148:151], v[180:183], v[22:25]
	v_mfma_f32_16x16x32_bf16 v[18:21], v[156:159], v[180:183], v[18:21]
	v_mfma_f32_16x16x32_bf16 v[6:9], v[148:151], v[188:191], v[6:9]
	v_mfma_f32_16x16x32_bf16 v[2:5], v[156:159], v[188:191], v[2:5]
	v_mfma_f32_16x16x32_bf16 v[54:57], v[152:155], v[168:171], v[54:57]
	v_mfma_f32_16x16x32_bf16 v[50:53], v[160:163], v[168:171], v[50:53]
	v_mfma_f32_16x16x32_bf16 v[38:41], v[152:155], v[176:179], v[38:41]
	v_mfma_f32_16x16x32_bf16 v[34:37], v[160:163], v[176:179], v[34:37]
	v_mfma_f32_16x16x32_bf16 v[22:25], v[152:155], v[184:187], v[22:25]
	v_mfma_f32_16x16x32_bf16 v[18:21], v[160:163], v[184:187], v[18:21]
	v_mfma_f32_16x16x32_bf16 v[6:9], v[152:155], v[212:215], v[6:9]
	v_mfma_f32_16x16x32_bf16 v[2:5], v[160:163], v[212:215], v[2:5]
	s_barrier
	s_add_u32 s20, s26, 0x158000
	s_addc_u32 s21, s27, 0
	s_add_i32 s2, 0, 0x18000
	s_add_i32 s43, 0, 0x1c000
	v_add_u32_e32 v142, s2, v240
	v_add_u32_e32 v160, s43, v240
	ds_read_b128 v[130:133], v142
	ds_read_b128 v[134:137], v142 offset:1024
	ds_read_b128 v[138:141], v142 offset:2048
	ds_read_b128 v[142:145], v142 offset:3072
	ds_read_b128 v[148:151], v160
	ds_read_b128 v[152:155], v160 offset:1024
	ds_read_b128 v[156:159], v160 offset:2048
	ds_read_b128 v[160:163], v160 offset:3072
	s_mov_b32 m0, s31
	ds_read_b128 v[164:167], v242 offset:32768
	ds_read_b128 v[168:171], v242 offset:33792
	ds_read_b128 v[172:175], v242 offset:34816
	ds_read_b128 v[176:179], v242 offset:35840
	ds_read_b128 v[180:183], v242 offset:36864
	ds_read_b128 v[184:187], v242 offset:37888
	ds_read_b128 v[188:191], v242 offset:38912
	ds_read_b128 v[212:215], v242 offset:39936
	s_mov_b32 m0, s1
	s_nop 0
	global_load_lds_dwordx4 v206, s[26:27]
	s_mov_b32 m0, s30
	s_nop 0
	global_load_lds_dwordx4 v194, s[26:27]
	s_mov_b32 m0, s31
	s_nop 0
	global_load_lds_dwordx4 v206, s[20:21]
	s_mov_b32 m0, s33
	s_nop 0
	global_load_lds_dwordx4 v194, s[20:21]
	s_waitcnt vmcnt(8)
	s_waitcnt lgkmcnt(0)
	s_barrier
	s_waitcnt lgkmcnt(0)
	v_mfma_f32_16x16x32_bf16 v[126:129], v[130:133], v[164:167], v[126:129]
	v_mfma_f32_16x16x32_bf16 v[122:125], v[138:141], v[164:167], v[122:125]
	v_mfma_f32_16x16x32_bf16 v[110:113], v[130:133], v[172:175], v[110:113]
	v_mfma_f32_16x16x32_bf16 v[106:109], v[138:141], v[172:175], v[106:109]
	v_mfma_f32_16x16x32_bf16 v[94:97], v[130:133], v[180:183], v[94:97]
	v_mfma_f32_16x16x32_bf16 v[90:93], v[138:141], v[180:183], v[90:93]
	v_mfma_f32_16x16x32_bf16 v[78:81], v[130:133], v[188:191], v[78:81]
	v_mfma_f32_16x16x32_bf16 v[74:77], v[138:141], v[188:191], v[74:77]
	v_mfma_f32_16x16x32_bf16 v[126:129], v[134:137], v[168:171], v[126:129]
	v_mfma_f32_16x16x32_bf16 v[122:125], v[142:145], v[168:171], v[122:125]
	v_mfma_f32_16x16x32_bf16 v[110:113], v[134:137], v[176:179], v[110:113]
	v_mfma_f32_16x16x32_bf16 v[106:109], v[142:145], v[176:179], v[106:109]
	v_mfma_f32_16x16x32_bf16 v[94:97], v[134:137], v[184:187], v[94:97]
	v_mfma_f32_16x16x32_bf16 v[90:93], v[142:145], v[184:187], v[90:93]
	v_mfma_f32_16x16x32_bf16 v[78:81], v[134:137], v[212:215], v[78:81]
	v_mfma_f32_16x16x32_bf16 v[74:77], v[142:145], v[212:215], v[74:77]
	v_mfma_f32_16x16x32_bf16 v[118:121], v[148:151], v[164:167], v[118:121]
	v_mfma_f32_16x16x32_bf16 v[114:117], v[156:159], v[164:167], v[114:117]
	v_mfma_f32_16x16x32_bf16 v[102:105], v[148:151], v[172:175], v[102:105]
	v_mfma_f32_16x16x32_bf16 v[98:101], v[156:159], v[172:175], v[98:101]
	v_mfma_f32_16x16x32_bf16 v[86:89], v[148:151], v[180:183], v[86:89]
	v_mfma_f32_16x16x32_bf16 v[82:85], v[156:159], v[180:183], v[82:85]
	v_mfma_f32_16x16x32_bf16 v[70:73], v[148:151], v[188:191], v[70:73]
	v_mfma_f32_16x16x32_bf16 v[66:69], v[156:159], v[188:191], v[66:69]
	v_mfma_f32_16x16x32_bf16 v[118:121], v[152:155], v[168:171], v[118:121]
	v_mfma_f32_16x16x32_bf16 v[114:117], v[160:163], v[168:171], v[114:117]
	v_mfma_f32_16x16x32_bf16 v[102:105], v[152:155], v[176:179], v[102:105]
	v_mfma_f32_16x16x32_bf16 v[98:101], v[160:163], v[176:179], v[98:101]
	v_mfma_f32_16x16x32_bf16 v[86:89], v[152:155], v[184:187], v[86:89]
	v_mfma_f32_16x16x32_bf16 v[82:85], v[160:163], v[184:187], v[82:85]
	v_mfma_f32_16x16x32_bf16 v[70:73], v[152:155], v[212:215], v[70:73]
	v_mfma_f32_16x16x32_bf16 v[66:69], v[160:163], v[212:215], v[66:69]
	s_barrier
	s_add_u32 s20, s24, 0x158080
	s_addc_u32 s21, s25, 0
	s_add_u32 s24, s24, 0x80
	s_addc_u32 s25, s25, 0
	s_add_i32 s2, s2, s0
	s_mov_b32 m0, s2
	ds_read_b128 v[164:167], v242 offset:49152
	ds_read_b128 v[168:171], v242 offset:50176
	ds_read_b128 v[172:175], v242 offset:51200
	ds_read_b128 v[176:179], v242 offset:52224
	ds_read_b128 v[180:183], v242 offset:53248
	ds_read_b128 v[184:187], v242 offset:54272
	ds_read_b128 v[188:191], v242 offset:55296
	ds_read_b128 v[212:215], v242 offset:56320
	global_load_lds_dwordx4 v0, s[24:25]
	s_add_i32 m0, s2, 0x2000
	s_add_i32 s2, s43, s0
	global_load_lds_dwordx4 v192, s[24:25]
	s_mov_b32 m0, s2
	s_nop 0
	global_load_lds_dwordx4 v0, s[20:21]
	s_add_i32 m0, s2, 0x2000
	s_nop 0
	global_load_lds_dwordx4 v192, s[20:21]
	s_waitcnt vmcnt(6)
	s_waitcnt lgkmcnt(0)
	s_barrier
	s_waitcnt lgkmcnt(0)
	v_mfma_f32_16x16x32_bf16 v[62:65], v[130:133], v[164:167], v[62:65]
	v_mfma_f32_16x16x32_bf16 v[58:61], v[138:141], v[164:167], v[58:61]
	v_mfma_f32_16x16x32_bf16 v[46:49], v[130:133], v[172:175], v[46:49]
	v_mfma_f32_16x16x32_bf16 v[42:45], v[138:141], v[172:175], v[42:45]
	v_mfma_f32_16x16x32_bf16 v[30:33], v[130:133], v[180:183], v[30:33]
	v_mfma_f32_16x16x32_bf16 v[26:29], v[138:141], v[180:183], v[26:29]
	v_mfma_f32_16x16x32_bf16 v[14:17], v[130:133], v[188:191], v[14:17]
	v_mfma_f32_16x16x32_bf16 v[10:13], v[138:141], v[188:191], v[10:13]
	v_mfma_f32_16x16x32_bf16 v[62:65], v[134:137], v[168:171], v[62:65]
	v_mfma_f32_16x16x32_bf16 v[58:61], v[142:145], v[168:171], v[58:61]
	v_mfma_f32_16x16x32_bf16 v[46:49], v[134:137], v[176:179], v[46:49]
	v_mfma_f32_16x16x32_bf16 v[42:45], v[142:145], v[176:179], v[42:45]
	v_mfma_f32_16x16x32_bf16 v[30:33], v[134:137], v[184:187], v[30:33]
	v_mfma_f32_16x16x32_bf16 v[26:29], v[142:145], v[184:187], v[26:29]
	v_mfma_f32_16x16x32_bf16 v[14:17], v[134:137], v[212:215], v[14:17]
	v_mfma_f32_16x16x32_bf16 v[10:13], v[142:145], v[212:215], v[10:13]
	v_mfma_f32_16x16x32_bf16 v[54:57], v[148:151], v[164:167], v[54:57]
	v_mfma_f32_16x16x32_bf16 v[50:53], v[156:159], v[164:167], v[50:53]
	v_mfma_f32_16x16x32_bf16 v[38:41], v[148:151], v[172:175], v[38:41]
	v_mfma_f32_16x16x32_bf16 v[34:37], v[156:159], v[172:175], v[34:37]
	v_mfma_f32_16x16x32_bf16 v[22:25], v[148:151], v[180:183], v[22:25]
	v_mfma_f32_16x16x32_bf16 v[18:21], v[156:159], v[180:183], v[18:21]
	v_mfma_f32_16x16x32_bf16 v[6:9], v[148:151], v[188:191], v[6:9]
	v_mfma_f32_16x16x32_bf16 v[2:5], v[156:159], v[188:191], v[2:5]
	v_mfma_f32_16x16x32_bf16 v[54:57], v[152:155], v[168:171], v[54:57]
	v_mfma_f32_16x16x32_bf16 v[50:53], v[160:163], v[168:171], v[50:53]
	v_mfma_f32_16x16x32_bf16 v[38:41], v[152:155], v[176:179], v[38:41]
	v_mfma_f32_16x16x32_bf16 v[34:37], v[160:163], v[176:179], v[34:37]
	v_mfma_f32_16x16x32_bf16 v[22:25], v[152:155], v[184:187], v[22:25]
	v_mfma_f32_16x16x32_bf16 v[18:21], v[160:163], v[184:187], v[18:21]
	v_mfma_f32_16x16x32_bf16 v[6:9], v[152:155], v[212:215], v[6:9]
	v_mfma_f32_16x16x32_bf16 v[2:5], v[160:163], v[212:215], v[2:5]
	s_barrier
	s_add_i32 s42, s42, 2
	s_add_u32 s40, s40, 0x100
	s_addc_u32 s41, s41, 0
	s_cmpk_gt_u32 s42, 0x53
	s_mov_b64 s[20:21], s[22:23]
	s_cbranch_scc0 .LBB0_322
	s_nop 0
	s_nop 0
	s_nop 0
	s_nop 0
	s_and_b64 vcc, exec, s[16:17]
	s_cbranch_vccz .LBB0_325
	s_barrier

.LBB0_408:
	s_add_u32 s2, s24, 0xfff80080
	s_addc_u32 s22, s25, -1
	s_add_i32 s45, 0, 0x10000
	s_cmp_eq_u32 s44, 28
	s_cselect_b32 s27, s17, s22
	s_cselect_b32 s26, s40, s2
	v_add_u32_e32 v144, s45, v148
	s_cselect_b32 s23, s15, s43
	s_cselect_b32 s22, s41, s42
	s_add_u32 s100, s24, 0xfff80000
	s_addc_u32 s101, s25, -1
	s_add_i32 s2, 0, 0x14000
	ds_read_b128 v[140:143], v144
	ds_read_b128 v[152:155], v144 offset:1024
	ds_read_b128 v[156:159], v144 offset:2048
	ds_read_b128 v[160:163], v144 offset:3072
	v_add_u32_e32 v144, s2, v148
	ds_read_b128 v[164:167], v144
	ds_read_b128 v[168:171], v144 offset:1024
	ds_read_b128 v[172:175], v144 offset:2048
	ds_read_b128 v[176:179], v144 offset:3072
	s_add_i32 m0, s29, 0xc000
	ds_read_b128 v[180:183], v151
	ds_read_b128 v[184:187], v151 offset:1024
	ds_read_b128 v[188:191], v151 offset:2048
	ds_read_b128 v[192:195], v151 offset:3072
	ds_read_b128 v[206:209], v151 offset:4096
	ds_read_b128 v[210:213], v151 offset:5120
	ds_read_b128 v[214:217], v151 offset:6144
	ds_read_b128 v[218:221], v151 offset:7168
	s_mov_b32 m0, s35
	s_nop 0
	global_load_lds_dwordx4 v136, s[100:101]
	s_mov_b32 m0, s36
	s_nop 0
	global_load_lds_dwordx4 v138, s[100:101]
	s_add_i32 m0, s29, 0xc000
	s_nop 0
	global_load_lds_dwordx4 v136, s[24:25]
	s_add_i32 m0, s29, 0xe000
	s_nop 0
	global_load_lds_dwordx4 v138, s[24:25]
	s_waitcnt vmcnt(8)
	s_waitcnt lgkmcnt(0)
	s_barrier
	s_waitcnt lgkmcnt(0)
	v_mfma_f32_16x16x32_bf16 v[126:129], v[140:143], v[180:183], v[126:129]
	v_mfma_f32_16x16x32_bf16 v[122:125], v[156:159], v[180:183], v[122:125]
	v_mfma_f32_16x16x32_bf16 v[110:113], v[140:143], v[188:191], v[110:113]
	v_mfma_f32_16x16x32_bf16 v[106:109], v[156:159], v[188:191], v[106:109]
	v_mfma_f32_16x16x32_bf16 v[94:97], v[140:143], v[206:209], v[94:97]
	v_mfma_f32_16x16x32_bf16 v[90:93], v[156:159], v[206:209], v[90:93]
	v_mfma_f32_16x16x32_bf16 v[78:81], v[140:143], v[214:217], v[78:81]
	v_mfma_f32_16x16x32_bf16 v[74:77], v[156:159], v[214:217], v[74:77]
	v_mfma_f32_16x16x32_bf16 v[126:129], v[152:155], v[184:187], v[126:129]
	v_mfma_f32_16x16x32_bf16 v[122:125], v[160:163], v[184:187], v[122:125]
	v_mfma_f32_16x16x32_bf16 v[110:113], v[152:155], v[192:195], v[110:113]
	v_mfma_f32_16x16x32_bf16 v[106:109], v[160:163], v[192:195], v[106:109]
	v_mfma_f32_16x16x32_bf16 v[94:97], v[152:155], v[210:213], v[94:97]
	v_mfma_f32_16x16x32_bf16 v[90:93], v[160:163], v[210:213], v[90:93]
	v_mfma_f32_16x16x32_bf16 v[78:81], v[152:155], v[218:221], v[78:81]
	v_mfma_f32_16x16x32_bf16 v[74:77], v[160:163], v[218:221], v[74:77]
	v_mfma_f32_16x16x32_bf16 v[118:121], v[164:167], v[180:183], v[118:121]
	v_mfma_f32_16x16x32_bf16 v[114:117], v[172:175], v[180:183], v[114:117]
	v_mfma_f32_16x16x32_bf16 v[102:105], v[164:167], v[188:191], v[102:105]
	v_mfma_f32_16x16x32_bf16 v[98:101], v[172:175], v[188:191], v[98:101]
	v_mfma_f32_16x16x32_bf16 v[86:89], v[164:167], v[206:209], v[86:89]
	v_mfma_f32_16x16x32_bf16 v[82:85], v[172:175], v[206:209], v[82:85]
	v_mfma_f32_16x16x32_bf16 v[70:73], v[164:167], v[214:217], v[70:73]
	v_mfma_f32_16x16x32_bf16 v[66:69], v[172:175], v[214:217], v[66:69]
	v_mfma_f32_16x16x32_bf16 v[118:121], v[168:171], v[184:187], v[118:121]
	v_mfma_f32_16x16x32_bf16 v[114:117], v[176:179], v[184:187], v[114:117]
	v_mfma_f32_16x16x32_bf16 v[102:105], v[168:171], v[192:195], v[102:105]
	v_mfma_f32_16x16x32_bf16 v[98:101], v[176:179], v[192:195], v[98:101]
	v_mfma_f32_16x16x32_bf16 v[86:89], v[168:171], v[210:213], v[86:89]
	v_mfma_f32_16x16x32_bf16 v[82:85], v[176:179], v[210:213], v[82:85]
	v_mfma_f32_16x16x32_bf16 v[70:73], v[168:171], v[218:221], v[70:73]
	v_mfma_f32_16x16x32_bf16 v[66:69], v[176:179], v[218:221], v[66:69]
	s_barrier
	s_add_u32 s46, s22, 0x80000
	s_addc_u32 s47, s23, 0
	s_add_i32 s45, s45, s28
	s_mov_b32 m0, s45
	ds_read_b128 v[180:183], v151 offset:16384
	ds_read_b128 v[184:187], v151 offset:17408
	ds_read_b128 v[188:191], v151 offset:18432
	ds_read_b128 v[192:195], v151 offset:19456
	ds_read_b128 v[206:209], v151 offset:20480
	ds_read_b128 v[210:213], v151 offset:21504
	ds_read_b128 v[214:217], v151 offset:22528
	ds_read_b128 v[218:221], v151 offset:23552
	global_load_lds_dwordx4 v0, s[22:23]
	s_add_i32 m0, s45, 0x2000
	s_add_i32 s2, s2, s28
	global_load_lds_dwordx4 v130, s[22:23]
	s_mov_b32 m0, s2
	s_nop 0
	global_load_lds_dwordx4 v0, s[46:47]
	s_add_i32 m0, s2, 0x2000
	s_nop 0
	global_load_lds_dwordx4 v130, s[46:47]
	s_waitcnt vmcnt(6)
	s_waitcnt lgkmcnt(0)
	s_barrier
	s_waitcnt lgkmcnt(0)
	v_mfma_f32_16x16x32_bf16 v[62:65], v[140:143], v[180:183], v[62:65]
	v_mfma_f32_16x16x32_bf16 v[58:61], v[156:159], v[180:183], v[58:61]
	v_mfma_f32_16x16x32_bf16 v[46:49], v[140:143], v[188:191], v[46:49]
	v_mfma_f32_16x16x32_bf16 v[42:45], v[156:159], v[188:191], v[42:45]
	v_mfma_f32_16x16x32_bf16 v[30:33], v[140:143], v[206:209], v[30:33]
	v_mfma_f32_16x16x32_bf16 v[26:29], v[156:159], v[206:209], v[26:29]
	v_mfma_f32_16x16x32_bf16 v[14:17], v[140:143], v[214:217], v[14:17]
	v_mfma_f32_16x16x32_bf16 v[10:13], v[156:159], v[214:217], v[10:13]
	v_mfma_f32_16x16x32_bf16 v[62:65], v[152:155], v[184:187], v[62:65]
	v_mfma_f32_16x16x32_bf16 v[58:61], v[160:163], v[184:187], v[58:61]
	v_mfma_f32_16x16x32_bf16 v[46:49], v[152:155], v[192:195], v[46:49]
	v_mfma_f32_16x16x32_bf16 v[42:45], v[160:163], v[192:195], v[42:45]
	v_mfma_f32_16x16x32_bf16 v[30:33], v[152:155], v[210:213], v[30:33]
	v_mfma_f32_16x16x32_bf16 v[26:29], v[160:163], v[210:213], v[26:29]
	v_mfma_f32_16x16x32_bf16 v[14:17], v[152:155], v[218:221], v[14:17]
	v_mfma_f32_16x16x32_bf16 v[10:13], v[160:163], v[218:221], v[10:13]
	v_mfma_f32_16x16x32_bf16 v[54:57], v[164:167], v[180:183], v[54:57]
	v_mfma_f32_16x16x32_bf16 v[50:53], v[172:175], v[180:183], v[50:53]
	v_mfma_f32_16x16x32_bf16 v[38:41], v[164:167], v[188:191], v[38:41]
	v_mfma_f32_16x16x32_bf16 v[34:37], v[172:175], v[188:191], v[34:37]
	v_mfma_f32_16x16x32_bf16 v[22:25], v[164:167], v[206:209], v[22:25]
	v_mfma_f32_16x16x32_bf16 v[18:21], v[172:175], v[206:209], v[18:21]
	v_mfma_f32_16x16x32_bf16 v[6:9], v[164:167], v[214:217], v[6:9]
	v_mfma_f32_16x16x32_bf16 v[2:5], v[172:175], v[214:217], v[2:5]
	v_mfma_f32_16x16x32_bf16 v[54:57], v[168:171], v[184:187], v[54:57]
	v_mfma_f32_16x16x32_bf16 v[50:53], v[176:179], v[184:187], v[50:53]
	v_mfma_f32_16x16x32_bf16 v[38:41], v[168:171], v[192:195], v[38:41]
	v_mfma_f32_16x16x32_bf16 v[34:37], v[176:179], v[192:195], v[34:37]
	v_mfma_f32_16x16x32_bf16 v[22:25], v[168:171], v[210:213], v[22:25]
	v_mfma_f32_16x16x32_bf16 v[18:21], v[176:179], v[210:213], v[18:21]
	v_mfma_f32_16x16x32_bf16 v[6:9], v[168:171], v[218:221], v[6:9]
	v_mfma_f32_16x16x32_bf16 v[2:5], v[176:179], v[218:221], v[2:5]
	s_barrier
	s_add_u32 s26, s26, 0x80000
	s_addc_u32 s27, s27, 0
	s_add_u32 s100, s26, 0xfff80000
	s_addc_u32 s101, s27, -1
	s_add_i32 s2, 0, 0x18000
	s_add_i32 s45, 0, 0x1c000
	v_add_u32_e32 v160, s2, v148
	v_add_u32_e32 v176, s45, v148
	ds_read_b128 v[140:143], v160
	ds_read_b128 v[152:155], v160 offset:1024
	ds_read_b128 v[156:159], v160 offset:2048
	ds_read_b128 v[160:163], v160 offset:3072
	ds_read_b128 v[164:167], v176
	ds_read_b128 v[168:171], v176 offset:1024
	ds_read_b128 v[172:175], v176 offset:2048
	ds_read_b128 v[176:179], v176 offset:3072
	s_mov_b32 m0, s31
	ds_read_b128 v[180:183], v151 offset:32768
	ds_read_b128 v[184:187], v151 offset:33792
	ds_read_b128 v[188:191], v151 offset:34816
	ds_read_b128 v[192:195], v151 offset:35840
	ds_read_b128 v[206:209], v151 offset:36864
	ds_read_b128 v[210:213], v151 offset:37888
	ds_read_b128 v[214:217], v151 offset:38912
	ds_read_b128 v[218:221], v151 offset:39936
	s_mov_b32 m0, s29
	s_nop 0
	global_load_lds_dwordx4 v134, s[100:101]
	s_mov_b32 m0, s30
	s_nop 0
	global_load_lds_dwordx4 v132, s[100:101]
	s_mov_b32 m0, s31
	s_nop 0
	global_load_lds_dwordx4 v134, s[26:27]
	s_mov_b32 m0, s33
	s_nop 0
	global_load_lds_dwordx4 v132, s[26:27]
	s_waitcnt vmcnt(8)
	s_waitcnt lgkmcnt(0)
	s_barrier
	s_waitcnt lgkmcnt(0)
	v_mfma_f32_16x16x32_bf16 v[126:129], v[140:143], v[180:183], v[126:129]
	v_mfma_f32_16x16x32_bf16 v[122:125], v[156:159], v[180:183], v[122:125]
	v_mfma_f32_16x16x32_bf16 v[110:113], v[140:143], v[188:191], v[110:113]
	v_mfma_f32_16x16x32_bf16 v[106:109], v[156:159], v[188:191], v[106:109]
	v_mfma_f32_16x16x32_bf16 v[94:97], v[140:143], v[206:209], v[94:97]
	v_mfma_f32_16x16x32_bf16 v[90:93], v[156:159], v[206:209], v[90:93]
	v_mfma_f32_16x16x32_bf16 v[78:81], v[140:143], v[214:217], v[78:81]
	v_mfma_f32_16x16x32_bf16 v[74:77], v[156:159], v[214:217], v[74:77]
	v_mfma_f32_16x16x32_bf16 v[126:129], v[152:155], v[184:187], v[126:129]
	v_mfma_f32_16x16x32_bf16 v[122:125], v[160:163], v[184:187], v[122:125]
	v_mfma_f32_16x16x32_bf16 v[110:113], v[152:155], v[192:195], v[110:113]
	v_mfma_f32_16x16x32_bf16 v[106:109], v[160:163], v[192:195], v[106:109]
	v_mfma_f32_16x16x32_bf16 v[94:97], v[152:155], v[210:213], v[94:97]
	v_mfma_f32_16x16x32_bf16 v[90:93], v[160:163], v[210:213], v[90:93]
	v_mfma_f32_16x16x32_bf16 v[78:81], v[152:155], v[218:221], v[78:81]
	v_mfma_f32_16x16x32_bf16 v[74:77], v[160:163], v[218:221], v[74:77]
	v_mfma_f32_16x16x32_bf16 v[118:121], v[164:167], v[180:183], v[118:121]
	v_mfma_f32_16x16x32_bf16 v[114:117], v[172:175], v[180:183], v[114:117]
	v_mfma_f32_16x16x32_bf16 v[102:105], v[164:167], v[188:191], v[102:105]
	v_mfma_f32_16x16x32_bf16 v[98:101], v[172:175], v[188:191], v[98:101]
	v_mfma_f32_16x16x32_bf16 v[86:89], v[164:167], v[206:209], v[86:89]
	v_mfma_f32_16x16x32_bf16 v[82:85], v[172:175], v[206:209], v[82:85]
	v_mfma_f32_16x16x32_bf16 v[70:73], v[164:167], v[214:217], v[70:73]
	v_mfma_f32_16x16x32_bf16 v[66:69], v[172:175], v[214:217], v[66:69]
	v_mfma_f32_16x16x32_bf16 v[118:121], v[168:171], v[184:187], v[118:121]
	v_mfma_f32_16x16x32_bf16 v[114:117], v[176:179], v[184:187], v[114:117]
	v_mfma_f32_16x16x32_bf16 v[102:105], v[168:171], v[192:195], v[102:105]
	v_mfma_f32_16x16x32_bf16 v[98:101], v[176:179], v[192:195], v[98:101]
	v_mfma_f32_16x16x32_bf16 v[86:89], v[168:171], v[210:213], v[86:89]
	v_mfma_f32_16x16x32_bf16 v[82:85], v[176:179], v[210:213], v[82:85]
	v_mfma_f32_16x16x32_bf16 v[70:73], v[168:171], v[218:221], v[70:73]
	v_mfma_f32_16x16x32_bf16 v[66:69], v[176:179], v[218:221], v[66:69]
	s_barrier
	s_add_u32 s22, s22, 0x80080
	s_addc_u32 s23, s23, 0
	s_add_u32 s46, s46, 0xfff80080
	s_addc_u32 s47, s47, -1
	s_add_i32 s2, s2, s28
	s_mov_b32 m0, s2
	ds_read_b128 v[180:183], v151 offset:49152
	ds_read_b128 v[184:187], v151 offset:50176
	ds_read_b128 v[188:191], v151 offset:51200
	ds_read_b128 v[192:195], v151 offset:52224
	ds_read_b128 v[206:209], v151 offset:53248
	ds_read_b128 v[210:213], v151 offset:54272
	ds_read_b128 v[214:217], v151 offset:55296
	ds_read_b128 v[218:221], v151 offset:56320
	global_load_lds_dwordx4 v0, s[46:47]
	s_add_i32 m0, s2, 0x2000
	s_add_i32 s2, s45, s28
	global_load_lds_dwordx4 v130, s[46:47]
	s_mov_b32 m0, s2
	s_nop 0
	global_load_lds_dwordx4 v0, s[22:23]
	s_add_i32 m0, s2, 0x2000
	s_nop 0
	global_load_lds_dwordx4 v130, s[22:23]
	s_waitcnt vmcnt(6)
	s_waitcnt lgkmcnt(0)
	s_barrier
	s_waitcnt lgkmcnt(0)
	v_mfma_f32_16x16x32_bf16 v[62:65], v[140:143], v[180:183], v[62:65]
	v_mfma_f32_16x16x32_bf16 v[58:61], v[156:159], v[180:183], v[58:61]
	v_mfma_f32_16x16x32_bf16 v[46:49], v[140:143], v[188:191], v[46:49]
	v_mfma_f32_16x16x32_bf16 v[42:45], v[156:159], v[188:191], v[42:45]
	v_mfma_f32_16x16x32_bf16 v[30:33], v[140:143], v[206:209], v[30:33]
	v_mfma_f32_16x16x32_bf16 v[26:29], v[156:159], v[206:209], v[26:29]
	v_mfma_f32_16x16x32_bf16 v[14:17], v[140:143], v[214:217], v[14:17]
	v_mfma_f32_16x16x32_bf16 v[10:13], v[156:159], v[214:217], v[10:13]
	v_mfma_f32_16x16x32_bf16 v[62:65], v[152:155], v[184:187], v[62:65]
	v_mfma_f32_16x16x32_bf16 v[58:61], v[160:163], v[184:187], v[58:61]
	v_mfma_f32_16x16x32_bf16 v[46:49], v[152:155], v[192:195], v[46:49]
	v_mfma_f32_16x16x32_bf16 v[42:45], v[160:163], v[192:195], v[42:45]
	v_mfma_f32_16x16x32_bf16 v[30:33], v[152:155], v[210:213], v[30:33]
	v_mfma_f32_16x16x32_bf16 v[26:29], v[160:163], v[210:213], v[26:29]
	v_mfma_f32_16x16x32_bf16 v[14:17], v[152:155], v[218:221], v[14:17]
	v_mfma_f32_16x16x32_bf16 v[10:13], v[160:163], v[218:221], v[10:13]
	v_mfma_f32_16x16x32_bf16 v[54:57], v[164:167], v[180:183], v[54:57]
	v_mfma_f32_16x16x32_bf16 v[50:53], v[172:175], v[180:183], v[50:53]
	v_mfma_f32_16x16x32_bf16 v[38:41], v[164:167], v[188:191], v[38:41]
	v_mfma_f32_16x16x32_bf16 v[34:37], v[172:175], v[188:191], v[34:37]
	v_mfma_f32_16x16x32_bf16 v[22:25], v[164:167], v[206:209], v[22:25]
	v_mfma_f32_16x16x32_bf16 v[18:21], v[172:175], v[206:209], v[18:21]
	v_mfma_f32_16x16x32_bf16 v[6:9], v[164:167], v[214:217], v[6:9]
	v_mfma_f32_16x16x32_bf16 v[2:5], v[172:175], v[214:217], v[2:5]
	v_mfma_f32_16x16x32_bf16 v[54:57], v[168:171], v[184:187], v[54:57]
	v_mfma_f32_16x16x32_bf16 v[50:53], v[176:179], v[184:187], v[50:53]
	v_mfma_f32_16x16x32_bf16 v[38:41], v[168:171], v[192:195], v[38:41]
	v_mfma_f32_16x16x32_bf16 v[34:37], v[176:179], v[192:195], v[34:37]
	v_mfma_f32_16x16x32_bf16 v[22:25], v[168:171], v[210:213], v[22:25]
	v_mfma_f32_16x16x32_bf16 v[18:21], v[176:179], v[210:213], v[18:21]
	v_mfma_f32_16x16x32_bf16 v[6:9], v[168:171], v[218:221], v[6:9]
	v_mfma_f32_16x16x32_bf16 v[2:5], v[176:179], v[218:221], v[2:5]
	s_barrier
	s_add_i32 s44, s44, 2
	s_add_u32 s24, s24, 0x100
	s_addc_u32 s25, s25, 0
	s_add_u32 s42, s42, 0x100
	s_addc_u32 s43, s43, 0
	s_cmp_gt_u32 s44, 29
	s_cbranch_scc0 .LBB0_408
	s_nop 0
	s_and_b64 vcc, exec, s[12:13]
	s_cbranch_vccz .LBB0_411
	s_barrier

.LBB0_440:
	s_add_u32 s2, s18, 0xfff80080
	s_addc_u32 s10, s19, -1
	s_add_i32 s47, 0, 0x10000
	s_cmp_eq_u32 s46, 28
	s_cselect_b32 s29, s25, s10
	s_cselect_b32 s28, s34, s2
	s_cselect_b32 s11, s23, s45
	s_cselect_b32 s10, s43, s44
	s_add_u32 s100, s18, 0xfff80000
	s_addc_u32 s101, s19, -1
	s_add_i32 s2, 0, 0x14000
	v_add_u32_e32 v154, s47, v162
	v_add_u32_e32 v184, s2, v162
	ds_read_b128 v[130:133], v154
	ds_read_b128 v[134:137], v154 offset:1024
	ds_read_b128 v[150:153], v154 offset:2048
	ds_read_b128 v[154:157], v154 offset:3072
	ds_read_b128 v[158:161], v184
	ds_read_b128 v[176:179], v184 offset:1024
	ds_read_b128 v[180:183], v184 offset:2048
	ds_read_b128 v[184:187], v184 offset:3072
	s_add_i32 m0, s31, 0xc000
	ds_read_b128 v[188:191], v175
	ds_read_b128 v[192:195], v175 offset:1024
	ds_read_b128 v[206:209], v175 offset:2048
	ds_read_b128 v[210:213], v175 offset:3072
	ds_read_b128 v[214:217], v175 offset:4096
	ds_read_b128 v[218:221], v175 offset:5120
	ds_read_b128 v[222:225], v175 offset:6144
	ds_read_b128 v[226:229], v175 offset:7168
	s_mov_b32 m0, s38
	s_nop 0
	global_load_lds_dwordx4 v144, s[100:101]
	s_mov_b32 m0, s39
	s_nop 0
	global_load_lds_dwordx4 v148, s[100:101]
	s_add_i32 m0, s31, 0xc000
	s_nop 0
	global_load_lds_dwordx4 v144, s[18:19]
	s_add_i32 m0, s31, 0xe000
	s_nop 0
	global_load_lds_dwordx4 v148, s[18:19]
	s_waitcnt vmcnt(8)
	s_waitcnt lgkmcnt(0)
	s_barrier
	s_waitcnt lgkmcnt(0)
	v_mfma_f32_16x16x32_bf16 v[126:129], v[130:133], v[188:191], v[126:129]
	v_mfma_f32_16x16x32_bf16 v[122:125], v[150:153], v[188:191], v[122:125]
	v_mfma_f32_16x16x32_bf16 v[110:113], v[130:133], v[206:209], v[110:113]
	v_mfma_f32_16x16x32_bf16 v[106:109], v[150:153], v[206:209], v[106:109]
	v_mfma_f32_16x16x32_bf16 v[94:97], v[130:133], v[214:217], v[94:97]
	v_mfma_f32_16x16x32_bf16 v[90:93], v[150:153], v[214:217], v[90:93]
	v_mfma_f32_16x16x32_bf16 v[78:81], v[130:133], v[222:225], v[78:81]
	v_mfma_f32_16x16x32_bf16 v[74:77], v[150:153], v[222:225], v[74:77]
	v_mfma_f32_16x16x32_bf16 v[126:129], v[134:137], v[192:195], v[126:129]
	v_mfma_f32_16x16x32_bf16 v[122:125], v[154:157], v[192:195], v[122:125]
	v_mfma_f32_16x16x32_bf16 v[110:113], v[134:137], v[210:213], v[110:113]
	v_mfma_f32_16x16x32_bf16 v[106:109], v[154:157], v[210:213], v[106:109]
	v_mfma_f32_16x16x32_bf16 v[94:97], v[134:137], v[218:221], v[94:97]
	v_mfma_f32_16x16x32_bf16 v[90:93], v[154:157], v[218:221], v[90:93]
	v_mfma_f32_16x16x32_bf16 v[78:81], v[134:137], v[226:229], v[78:81]
	v_mfma_f32_16x16x32_bf16 v[74:77], v[154:157], v[226:229], v[74:77]
	v_mfma_f32_16x16x32_bf16 v[118:121], v[158:161], v[188:191], v[118:121]
	v_mfma_f32_16x16x32_bf16 v[114:117], v[180:183], v[188:191], v[114:117]
	v_mfma_f32_16x16x32_bf16 v[102:105], v[158:161], v[206:209], v[102:105]
	v_mfma_f32_16x16x32_bf16 v[98:101], v[180:183], v[206:209], v[98:101]
	v_mfma_f32_16x16x32_bf16 v[86:89], v[158:161], v[214:217], v[86:89]
	v_mfma_f32_16x16x32_bf16 v[82:85], v[180:183], v[214:217], v[82:85]
	v_mfma_f32_16x16x32_bf16 v[70:73], v[158:161], v[222:225], v[70:73]
	v_mfma_f32_16x16x32_bf16 v[66:69], v[180:183], v[222:225], v[66:69]
	v_mfma_f32_16x16x32_bf16 v[118:121], v[176:179], v[192:195], v[118:121]
	v_mfma_f32_16x16x32_bf16 v[114:117], v[184:187], v[192:195], v[114:117]
	v_mfma_f32_16x16x32_bf16 v[102:105], v[176:179], v[210:213], v[102:105]
	v_mfma_f32_16x16x32_bf16 v[98:101], v[184:187], v[210:213], v[98:101]
	v_mfma_f32_16x16x32_bf16 v[86:89], v[176:179], v[218:221], v[86:89]
	v_mfma_f32_16x16x32_bf16 v[82:85], v[184:187], v[218:221], v[82:85]
	v_mfma_f32_16x16x32_bf16 v[70:73], v[176:179], v[226:229], v[70:73]
	v_mfma_f32_16x16x32_bf16 v[66:69], v[184:187], v[226:229], v[66:69]
	s_barrier
	s_add_u32 s52, s10, 0x80000
	s_addc_u32 s53, s11, 0
	s_add_i32 s47, s47, s30
	s_mov_b32 m0, s47
	ds_read_b128 v[188:191], v175 offset:16384
	ds_read_b128 v[192:195], v175 offset:17408
	ds_read_b128 v[206:209], v175 offset:18432
	ds_read_b128 v[210:213], v175 offset:19456
	ds_read_b128 v[214:217], v175 offset:20480
	ds_read_b128 v[218:221], v175 offset:21504
	ds_read_b128 v[222:225], v175 offset:22528
	ds_read_b128 v[226:229], v175 offset:23552
	global_load_lds_dwordx4 v0, s[10:11]
	s_add_i32 m0, s47, 0x2000
	s_add_i32 s2, s2, s30
	global_load_lds_dwordx4 v138, s[10:11]
	s_mov_b32 m0, s2
	s_nop 0
	global_load_lds_dwordx4 v0, s[52:53]
	s_add_i32 m0, s2, 0x2000
	s_nop 0
	global_load_lds_dwordx4 v138, s[52:53]
	s_waitcnt vmcnt(6)
	s_waitcnt lgkmcnt(0)
	s_barrier
	s_waitcnt lgkmcnt(0)
	v_mfma_f32_16x16x32_bf16 v[62:65], v[130:133], v[188:191], v[62:65]
	v_mfma_f32_16x16x32_bf16 v[58:61], v[150:153], v[188:191], v[58:61]
	v_mfma_f32_16x16x32_bf16 v[46:49], v[130:133], v[206:209], v[46:49]
	v_mfma_f32_16x16x32_bf16 v[42:45], v[150:153], v[206:209], v[42:45]
	v_mfma_f32_16x16x32_bf16 v[30:33], v[130:133], v[214:217], v[30:33]
	v_mfma_f32_16x16x32_bf16 v[26:29], v[150:153], v[214:217], v[26:29]
	v_mfma_f32_16x16x32_bf16 v[14:17], v[130:133], v[222:225], v[14:17]
	v_mfma_f32_16x16x32_bf16 v[10:13], v[150:153], v[222:225], v[10:13]
	v_mfma_f32_16x16x32_bf16 v[62:65], v[134:137], v[192:195], v[62:65]
	v_mfma_f32_16x16x32_bf16 v[58:61], v[154:157], v[192:195], v[58:61]
	v_mfma_f32_16x16x32_bf16 v[46:49], v[134:137], v[210:213], v[46:49]
	v_mfma_f32_16x16x32_bf16 v[42:45], v[154:157], v[210:213], v[42:45]
	v_mfma_f32_16x16x32_bf16 v[30:33], v[134:137], v[218:221], v[30:33]
	v_mfma_f32_16x16x32_bf16 v[26:29], v[154:157], v[218:221], v[26:29]
	v_mfma_f32_16x16x32_bf16 v[14:17], v[134:137], v[226:229], v[14:17]
	v_mfma_f32_16x16x32_bf16 v[10:13], v[154:157], v[226:229], v[10:13]
	v_mfma_f32_16x16x32_bf16 v[54:57], v[158:161], v[188:191], v[54:57]
	v_mfma_f32_16x16x32_bf16 v[50:53], v[180:183], v[188:191], v[50:53]
	v_mfma_f32_16x16x32_bf16 v[38:41], v[158:161], v[206:209], v[38:41]
	v_mfma_f32_16x16x32_bf16 v[34:37], v[180:183], v[206:209], v[34:37]
	v_mfma_f32_16x16x32_bf16 v[22:25], v[158:161], v[214:217], v[22:25]
	v_mfma_f32_16x16x32_bf16 v[18:21], v[180:183], v[214:217], v[18:21]
	v_mfma_f32_16x16x32_bf16 v[6:9], v[158:161], v[222:225], v[6:9]
	v_mfma_f32_16x16x32_bf16 v[2:5], v[180:183], v[222:225], v[2:5]
	v_mfma_f32_16x16x32_bf16 v[54:57], v[176:179], v[192:195], v[54:57]
	v_mfma_f32_16x16x32_bf16 v[50:53], v[184:187], v[192:195], v[50:53]
	v_mfma_f32_16x16x32_bf16 v[38:41], v[176:179], v[210:213], v[38:41]
	v_mfma_f32_16x16x32_bf16 v[34:37], v[184:187], v[210:213], v[34:37]
	v_mfma_f32_16x16x32_bf16 v[22:25], v[176:179], v[218:221], v[22:25]
	v_mfma_f32_16x16x32_bf16 v[18:21], v[184:187], v[218:221], v[18:21]
	v_mfma_f32_16x16x32_bf16 v[6:9], v[176:179], v[226:229], v[6:9]
	v_mfma_f32_16x16x32_bf16 v[2:5], v[184:187], v[226:229], v[2:5]
	s_barrier
	s_add_u32 s28, s28, 0x80000
	s_addc_u32 s29, s29, 0
	s_add_u32 s100, s28, 0xfff80000
	s_addc_u32 s101, s29, -1
	s_add_i32 s2, 0, 0x18000
	s_add_i32 s47, 0, 0x1c000
	v_add_u32_e32 v154, s2, v162
	v_add_u32_e32 v184, s47, v162
	ds_read_b128 v[130:133], v154
	ds_read_b128 v[134:137], v154 offset:1024
	ds_read_b128 v[150:153], v154 offset:2048
	ds_read_b128 v[154:157], v154 offset:3072
	ds_read_b128 v[158:161], v184
	ds_read_b128 v[176:179], v184 offset:1024
	ds_read_b128 v[180:183], v184 offset:2048
	ds_read_b128 v[184:187], v184 offset:3072
	s_mov_b32 m0, s36
	ds_read_b128 v[188:191], v175 offset:32768
	ds_read_b128 v[192:195], v175 offset:33792
	ds_read_b128 v[206:209], v175 offset:34816
	ds_read_b128 v[210:213], v175 offset:35840
	ds_read_b128 v[214:217], v175 offset:36864
	ds_read_b128 v[218:221], v175 offset:37888
	ds_read_b128 v[222:225], v175 offset:38912
	ds_read_b128 v[226:229], v175 offset:39936
	s_mov_b32 m0, s31
	s_nop 0
	global_load_lds_dwordx4 v142, s[100:101]
	s_mov_b32 m0, s35
	s_nop 0
	global_load_lds_dwordx4 v140, s[100:101]
	s_mov_b32 m0, s36
	s_nop 0
	global_load_lds_dwordx4 v142, s[28:29]
	s_mov_b32 m0, s37
	s_nop 0
	global_load_lds_dwordx4 v140, s[28:29]
	s_waitcnt vmcnt(8)
	s_waitcnt lgkmcnt(0)
	s_barrier
	s_waitcnt lgkmcnt(0)
	v_mfma_f32_16x16x32_bf16 v[126:129], v[130:133], v[188:191], v[126:129]
	v_mfma_f32_16x16x32_bf16 v[122:125], v[150:153], v[188:191], v[122:125]
	v_mfma_f32_16x16x32_bf16 v[110:113], v[130:133], v[206:209], v[110:113]
	v_mfma_f32_16x16x32_bf16 v[106:109], v[150:153], v[206:209], v[106:109]
	v_mfma_f32_16x16x32_bf16 v[94:97], v[130:133], v[214:217], v[94:97]
	v_mfma_f32_16x16x32_bf16 v[90:93], v[150:153], v[214:217], v[90:93]
	v_mfma_f32_16x16x32_bf16 v[78:81], v[130:133], v[222:225], v[78:81]
	v_mfma_f32_16x16x32_bf16 v[74:77], v[150:153], v[222:225], v[74:77]
	v_mfma_f32_16x16x32_bf16 v[126:129], v[134:137], v[192:195], v[126:129]
	v_mfma_f32_16x16x32_bf16 v[122:125], v[154:157], v[192:195], v[122:125]
	v_mfma_f32_16x16x32_bf16 v[110:113], v[134:137], v[210:213], v[110:113]
	v_mfma_f32_16x16x32_bf16 v[106:109], v[154:157], v[210:213], v[106:109]
	v_mfma_f32_16x16x32_bf16 v[94:97], v[134:137], v[218:221], v[94:97]
	v_mfma_f32_16x16x32_bf16 v[90:93], v[154:157], v[218:221], v[90:93]
	v_mfma_f32_16x16x32_bf16 v[78:81], v[134:137], v[226:229], v[78:81]
	v_mfma_f32_16x16x32_bf16 v[74:77], v[154:157], v[226:229], v[74:77]
	v_mfma_f32_16x16x32_bf16 v[118:121], v[158:161], v[188:191], v[118:121]
	v_mfma_f32_16x16x32_bf16 v[114:117], v[180:183], v[188:191], v[114:117]
	v_mfma_f32_16x16x32_bf16 v[102:105], v[158:161], v[206:209], v[102:105]
	v_mfma_f32_16x16x32_bf16 v[98:101], v[180:183], v[206:209], v[98:101]
	v_mfma_f32_16x16x32_bf16 v[86:89], v[158:161], v[214:217], v[86:89]
	v_mfma_f32_16x16x32_bf16 v[82:85], v[180:183], v[214:217], v[82:85]
	v_mfma_f32_16x16x32_bf16 v[70:73], v[158:161], v[222:225], v[70:73]
	v_mfma_f32_16x16x32_bf16 v[66:69], v[180:183], v[222:225], v[66:69]
	v_mfma_f32_16x16x32_bf16 v[118:121], v[176:179], v[192:195], v[118:121]
	v_mfma_f32_16x16x32_bf16 v[114:117], v[184:187], v[192:195], v[114:117]
	v_mfma_f32_16x16x32_bf16 v[102:105], v[176:179], v[210:213], v[102:105]
	v_mfma_f32_16x16x32_bf16 v[98:101], v[184:187], v[210:213], v[98:101]
	v_mfma_f32_16x16x32_bf16 v[86:89], v[176:179], v[218:221], v[86:89]
	v_mfma_f32_16x16x32_bf16 v[82:85], v[184:187], v[218:221], v[82:85]
	v_mfma_f32_16x16x32_bf16 v[70:73], v[176:179], v[226:229], v[70:73]
	v_mfma_f32_16x16x32_bf16 v[66:69], v[184:187], v[226:229], v[66:69]
	s_barrier
	s_add_u32 s10, s10, 0x80080
	s_addc_u32 s11, s11, 0
	s_add_u32 s52, s52, 0xfff80080
	s_addc_u32 s53, s53, -1
	s_add_i32 s2, s2, s30
	s_mov_b32 m0, s2
	ds_read_b128 v[188:191], v175 offset:49152
	ds_read_b128 v[192:195], v175 offset:50176
	ds_read_b128 v[206:209], v175 offset:51200
	ds_read_b128 v[210:213], v175 offset:52224
	ds_read_b128 v[214:217], v175 offset:53248
	ds_read_b128 v[218:221], v175 offset:54272
	ds_read_b128 v[222:225], v175 offset:55296
	ds_read_b128 v[226:229], v175 offset:56320
	global_load_lds_dwordx4 v0, s[52:53]
	s_add_i32 m0, s2, 0x2000
	s_add_i32 s2, s47, s30
	global_load_lds_dwordx4 v138, s[52:53]
	s_mov_b32 m0, s2
	s_nop 0
	global_load_lds_dwordx4 v0, s[10:11]
	s_add_i32 m0, s2, 0x2000
	s_nop 0
	global_load_lds_dwordx4 v138, s[10:11]
	s_waitcnt vmcnt(6)
	s_waitcnt lgkmcnt(0)
	s_barrier
	s_waitcnt lgkmcnt(0)
	v_mfma_f32_16x16x32_bf16 v[62:65], v[130:133], v[188:191], v[62:65]
	v_mfma_f32_16x16x32_bf16 v[58:61], v[150:153], v[188:191], v[58:61]
	v_mfma_f32_16x16x32_bf16 v[46:49], v[130:133], v[206:209], v[46:49]
	v_mfma_f32_16x16x32_bf16 v[42:45], v[150:153], v[206:209], v[42:45]
	v_mfma_f32_16x16x32_bf16 v[30:33], v[130:133], v[214:217], v[30:33]
	v_mfma_f32_16x16x32_bf16 v[26:29], v[150:153], v[214:217], v[26:29]
	v_mfma_f32_16x16x32_bf16 v[14:17], v[130:133], v[222:225], v[14:17]
	v_mfma_f32_16x16x32_bf16 v[10:13], v[150:153], v[222:225], v[10:13]
	v_mfma_f32_16x16x32_bf16 v[62:65], v[134:137], v[192:195], v[62:65]
	v_mfma_f32_16x16x32_bf16 v[58:61], v[154:157], v[192:195], v[58:61]
	v_mfma_f32_16x16x32_bf16 v[46:49], v[134:137], v[210:213], v[46:49]
	v_mfma_f32_16x16x32_bf16 v[42:45], v[154:157], v[210:213], v[42:45]
	v_mfma_f32_16x16x32_bf16 v[30:33], v[134:137], v[218:221], v[30:33]
	v_mfma_f32_16x16x32_bf16 v[26:29], v[154:157], v[218:221], v[26:29]
	v_mfma_f32_16x16x32_bf16 v[14:17], v[134:137], v[226:229], v[14:17]
	v_mfma_f32_16x16x32_bf16 v[10:13], v[154:157], v[226:229], v[10:13]
	v_mfma_f32_16x16x32_bf16 v[54:57], v[158:161], v[188:191], v[54:57]
	v_mfma_f32_16x16x32_bf16 v[50:53], v[180:183], v[188:191], v[50:53]
	v_mfma_f32_16x16x32_bf16 v[38:41], v[158:161], v[206:209], v[38:41]
	v_mfma_f32_16x16x32_bf16 v[34:37], v[180:183], v[206:209], v[34:37]
	v_mfma_f32_16x16x32_bf16 v[22:25], v[158:161], v[214:217], v[22:25]
	v_mfma_f32_16x16x32_bf16 v[18:21], v[180:183], v[214:217], v[18:21]
	v_mfma_f32_16x16x32_bf16 v[6:9], v[158:161], v[222:225], v[6:9]
	v_mfma_f32_16x16x32_bf16 v[2:5], v[180:183], v[222:225], v[2:5]
	v_mfma_f32_16x16x32_bf16 v[54:57], v[176:179], v[192:195], v[54:57]
	v_mfma_f32_16x16x32_bf16 v[50:53], v[184:187], v[192:195], v[50:53]
	v_mfma_f32_16x16x32_bf16 v[38:41], v[176:179], v[210:213], v[38:41]
	v_mfma_f32_16x16x32_bf16 v[34:37], v[184:187], v[210:213], v[34:37]
	v_mfma_f32_16x16x32_bf16 v[22:25], v[176:179], v[218:221], v[22:25]
	v_mfma_f32_16x16x32_bf16 v[18:21], v[184:187], v[218:221], v[18:21]
	v_mfma_f32_16x16x32_bf16 v[6:9], v[176:179], v[226:229], v[6:9]
	v_mfma_f32_16x16x32_bf16 v[2:5], v[184:187], v[226:229], v[2:5]
	s_barrier
	s_add_i32 s46, s46, 2
	s_add_u32 s18, s18, 0x100
	s_addc_u32 s19, s19, 0
	s_add_u32 s44, s44, 0x100
	s_addc_u32 s45, s45, 0
	s_cmp_gt_u32 s46, 29
	s_cbranch_scc0 .LBB0_440
	s_nop 0
	s_and_b64 vcc, exec, s[20:21]
	s_cbranch_vccz .LBB0_443
	s_barrier

.LBB0_1102:
	s_add_u32 s2, s22, 0xfff80080
	s_addc_u32 s20, s23, -1
	s_add_i32 s45, 0, 0x10000
	s_cmp_eq_u32 s44, 28
	s_cselect_b32 s25, s15, s20
	s_cselect_b32 s24, s40, s2
	s_cselect_b32 s21, s13, s43
	s_cselect_b32 s20, s41, s42
	s_add_u32 s100, s22, 0xfff80000
	s_addc_u32 s101, s23, -1
	s_add_i32 s2, 0, 0x14000
	v_add_u32_e32 v142, s45, v226
	v_add_u32_e32 v160, s2, v226
	ds_read_b128 v[130:133], v142
	ds_read_b128 v[134:137], v142 offset:1024
	ds_read_b128 v[138:141], v142 offset:2048
	ds_read_b128 v[142:145], v142 offset:3072
	ds_read_b128 v[148:151], v160
	ds_read_b128 v[152:155], v160 offset:1024
	ds_read_b128 v[156:159], v160 offset:2048
	ds_read_b128 v[160:163], v160 offset:3072
	s_add_i32 m0, s30, 0xc000
	ds_read_b128 v[164:167], v228
	ds_read_b128 v[168:171], v228 offset:1024
	ds_read_b128 v[172:175], v228 offset:2048
	ds_read_b128 v[176:179], v228 offset:3072
	ds_read_b128 v[180:183], v228 offset:4096
	ds_read_b128 v[184:187], v228 offset:5120
	ds_read_b128 v[208:211], v228 offset:6144
	ds_read_b128 v[212:215], v228 offset:7168
	s_mov_b32 m0, s38
	s_nop 0
	global_load_lds_dwordx4 v194, s[100:101]
	s_mov_b32 m0, s39
	s_nop 0
	global_load_lds_dwordx4 v206, s[100:101]
	s_add_i32 m0, s30, 0xc000
	s_nop 0
	global_load_lds_dwordx4 v194, s[22:23]
	s_add_i32 m0, s30, 0xe000
	s_nop 0
	global_load_lds_dwordx4 v206, s[22:23]
	s_waitcnt vmcnt(8)
	s_waitcnt lgkmcnt(0)
	s_barrier
	s_waitcnt lgkmcnt(0)
	v_mfma_f32_16x16x32_bf16 v[126:129], v[130:133], v[164:167], v[126:129]
	v_mfma_f32_16x16x32_bf16 v[122:125], v[138:141], v[164:167], v[122:125]
	v_mfma_f32_16x16x32_bf16 v[110:113], v[130:133], v[172:175], v[110:113]
	v_mfma_f32_16x16x32_bf16 v[106:109], v[138:141], v[172:175], v[106:109]
	v_mfma_f32_16x16x32_bf16 v[94:97], v[130:133], v[180:183], v[94:97]
	v_mfma_f32_16x16x32_bf16 v[90:93], v[138:141], v[180:183], v[90:93]
	v_mfma_f32_16x16x32_bf16 v[78:81], v[130:133], v[208:211], v[78:81]
	v_mfma_f32_16x16x32_bf16 v[74:77], v[138:141], v[208:211], v[74:77]
	v_mfma_f32_16x16x32_bf16 v[126:129], v[134:137], v[168:171], v[126:129]
	v_mfma_f32_16x16x32_bf16 v[122:125], v[142:145], v[168:171], v[122:125]
	v_mfma_f32_16x16x32_bf16 v[110:113], v[134:137], v[176:179], v[110:113]
	v_mfma_f32_16x16x32_bf16 v[106:109], v[142:145], v[176:179], v[106:109]
	v_mfma_f32_16x16x32_bf16 v[94:97], v[134:137], v[184:187], v[94:97]
	v_mfma_f32_16x16x32_bf16 v[90:93], v[142:145], v[184:187], v[90:93]
	v_mfma_f32_16x16x32_bf16 v[78:81], v[134:137], v[212:215], v[78:81]
	v_mfma_f32_16x16x32_bf16 v[74:77], v[142:145], v[212:215], v[74:77]
	v_mfma_f32_16x16x32_bf16 v[118:121], v[148:151], v[164:167], v[118:121]
	v_mfma_f32_16x16x32_bf16 v[114:117], v[156:159], v[164:167], v[114:117]
	v_mfma_f32_16x16x32_bf16 v[102:105], v[148:151], v[172:175], v[102:105]
	v_mfma_f32_16x16x32_bf16 v[98:101], v[156:159], v[172:175], v[98:101]
	v_mfma_f32_16x16x32_bf16 v[86:89], v[148:151], v[180:183], v[86:89]
	v_mfma_f32_16x16x32_bf16 v[82:85], v[156:159], v[180:183], v[82:85]
	v_mfma_f32_16x16x32_bf16 v[70:73], v[148:151], v[208:211], v[70:73]
	v_mfma_f32_16x16x32_bf16 v[66:69], v[156:159], v[208:211], v[66:69]
	v_mfma_f32_16x16x32_bf16 v[118:121], v[152:155], v[168:171], v[118:121]
	v_mfma_f32_16x16x32_bf16 v[114:117], v[160:163], v[168:171], v[114:117]
	v_mfma_f32_16x16x32_bf16 v[102:105], v[152:155], v[176:179], v[102:105]
	v_mfma_f32_16x16x32_bf16 v[98:101], v[160:163], v[176:179], v[98:101]
	v_mfma_f32_16x16x32_bf16 v[86:89], v[152:155], v[184:187], v[86:89]
	v_mfma_f32_16x16x32_bf16 v[82:85], v[160:163], v[184:187], v[82:85]
	v_mfma_f32_16x16x32_bf16 v[70:73], v[152:155], v[212:215], v[70:73]
	v_mfma_f32_16x16x32_bf16 v[66:69], v[160:163], v[212:215], v[66:69]
	s_barrier
	s_add_u32 s46, s20, 0x80000
	s_addc_u32 s47, s21, 0
	s_add_i32 s45, s45, s29
	s_mov_b32 m0, s45
	ds_read_b128 v[164:167], v228 offset:16384
	ds_read_b128 v[168:171], v228 offset:17408
	ds_read_b128 v[172:175], v228 offset:18432
	ds_read_b128 v[176:179], v228 offset:19456
	ds_read_b128 v[180:183], v228 offset:20480
	ds_read_b128 v[184:187], v228 offset:21504
	ds_read_b128 v[208:211], v228 offset:22528
	ds_read_b128 v[212:215], v228 offset:23552
	global_load_lds_dwordx4 v0, s[20:21]
	s_add_i32 m0, s45, 0x2000
	s_add_i32 s2, s2, s29
	global_load_lds_dwordx4 v188, s[20:21]
	s_mov_b32 m0, s2
	s_nop 0
	global_load_lds_dwordx4 v0, s[46:47]
	s_add_i32 m0, s2, 0x2000
	s_nop 0
	global_load_lds_dwordx4 v188, s[46:47]
	s_waitcnt vmcnt(6)
	s_waitcnt lgkmcnt(0)
	s_barrier
	s_waitcnt lgkmcnt(0)
	v_mfma_f32_16x16x32_bf16 v[62:65], v[130:133], v[164:167], v[62:65]
	v_mfma_f32_16x16x32_bf16 v[58:61], v[138:141], v[164:167], v[58:61]
	v_mfma_f32_16x16x32_bf16 v[46:49], v[130:133], v[172:175], v[46:49]
	v_mfma_f32_16x16x32_bf16 v[42:45], v[138:141], v[172:175], v[42:45]
	v_mfma_f32_16x16x32_bf16 v[30:33], v[130:133], v[180:183], v[30:33]
	v_mfma_f32_16x16x32_bf16 v[26:29], v[138:141], v[180:183], v[26:29]
	v_mfma_f32_16x16x32_bf16 v[14:17], v[130:133], v[208:211], v[14:17]
	v_mfma_f32_16x16x32_bf16 v[10:13], v[138:141], v[208:211], v[10:13]
	v_mfma_f32_16x16x32_bf16 v[62:65], v[134:137], v[168:171], v[62:65]
	v_mfma_f32_16x16x32_bf16 v[58:61], v[142:145], v[168:171], v[58:61]
	v_mfma_f32_16x16x32_bf16 v[46:49], v[134:137], v[176:179], v[46:49]
	v_mfma_f32_16x16x32_bf16 v[42:45], v[142:145], v[176:179], v[42:45]
	v_mfma_f32_16x16x32_bf16 v[30:33], v[134:137], v[184:187], v[30:33]
	v_mfma_f32_16x16x32_bf16 v[26:29], v[142:145], v[184:187], v[26:29]
	v_mfma_f32_16x16x32_bf16 v[14:17], v[134:137], v[212:215], v[14:17]
	v_mfma_f32_16x16x32_bf16 v[10:13], v[142:145], v[212:215], v[10:13]
	v_mfma_f32_16x16x32_bf16 v[54:57], v[148:151], v[164:167], v[54:57]
	v_mfma_f32_16x16x32_bf16 v[50:53], v[156:159], v[164:167], v[50:53]
	v_mfma_f32_16x16x32_bf16 v[38:41], v[148:151], v[172:175], v[38:41]
	v_mfma_f32_16x16x32_bf16 v[34:37], v[156:159], v[172:175], v[34:37]
	v_mfma_f32_16x16x32_bf16 v[22:25], v[148:151], v[180:183], v[22:25]
	v_mfma_f32_16x16x32_bf16 v[18:21], v[156:159], v[180:183], v[18:21]
	v_mfma_f32_16x16x32_bf16 v[6:9], v[148:151], v[208:211], v[6:9]
	v_mfma_f32_16x16x32_bf16 v[2:5], v[156:159], v[208:211], v[2:5]
	v_mfma_f32_16x16x32_bf16 v[54:57], v[152:155], v[168:171], v[54:57]
	v_mfma_f32_16x16x32_bf16 v[50:53], v[160:163], v[168:171], v[50:53]
	v_mfma_f32_16x16x32_bf16 v[38:41], v[152:155], v[176:179], v[38:41]
	v_mfma_f32_16x16x32_bf16 v[34:37], v[160:163], v[176:179], v[34:37]
	v_mfma_f32_16x16x32_bf16 v[22:25], v[152:155], v[184:187], v[22:25]
	v_mfma_f32_16x16x32_bf16 v[18:21], v[160:163], v[184:187], v[18:21]
	v_mfma_f32_16x16x32_bf16 v[6:9], v[152:155], v[212:215], v[6:9]
	v_mfma_f32_16x16x32_bf16 v[2:5], v[160:163], v[212:215], v[2:5]
	s_barrier
	s_add_u32 s24, s24, 0x80000
	s_addc_u32 s25, s25, 0
	s_add_u32 s100, s24, 0xfff80000
	s_addc_u32 s101, s25, -1
	s_add_i32 s2, 0, 0x18000
	s_add_i32 s45, 0, 0x1c000
	v_add_u32_e32 v142, s2, v226
	v_add_u32_e32 v160, s45, v226
	ds_read_b128 v[130:133], v142
	ds_read_b128 v[134:137], v142 offset:1024
	ds_read_b128 v[138:141], v142 offset:2048
	ds_read_b128 v[142:145], v142 offset:3072
	ds_read_b128 v[148:151], v160
	ds_read_b128 v[152:155], v160 offset:1024
	ds_read_b128 v[156:159], v160 offset:2048
	ds_read_b128 v[160:163], v160 offset:3072
	s_mov_b32 m0, s35
	ds_read_b128 v[164:167], v228 offset:32768
	ds_read_b128 v[168:171], v228 offset:33792
	ds_read_b128 v[172:175], v228 offset:34816
	ds_read_b128 v[176:179], v228 offset:35840
	ds_read_b128 v[180:183], v228 offset:36864
	ds_read_b128 v[184:187], v228 offset:37888
	ds_read_b128 v[208:211], v228 offset:38912
	ds_read_b128 v[212:215], v228 offset:39936
	s_mov_b32 m0, s30
	s_nop 0
	global_load_lds_dwordx4 v192, s[100:101]
	s_mov_b32 m0, s31
	s_nop 0
	global_load_lds_dwordx4 v190, s[100:101]
	s_mov_b32 m0, s35
	s_nop 0
	global_load_lds_dwordx4 v192, s[24:25]
	s_mov_b32 m0, s36
	s_nop 0
	global_load_lds_dwordx4 v190, s[24:25]
	s_waitcnt vmcnt(8)
	s_waitcnt lgkmcnt(0)
	s_barrier
	s_waitcnt lgkmcnt(0)
	v_mfma_f32_16x16x32_bf16 v[126:129], v[130:133], v[164:167], v[126:129]
	v_mfma_f32_16x16x32_bf16 v[122:125], v[138:141], v[164:167], v[122:125]
	v_mfma_f32_16x16x32_bf16 v[110:113], v[130:133], v[172:175], v[110:113]
	v_mfma_f32_16x16x32_bf16 v[106:109], v[138:141], v[172:175], v[106:109]
	v_mfma_f32_16x16x32_bf16 v[94:97], v[130:133], v[180:183], v[94:97]
	v_mfma_f32_16x16x32_bf16 v[90:93], v[138:141], v[180:183], v[90:93]
	v_mfma_f32_16x16x32_bf16 v[78:81], v[130:133], v[208:211], v[78:81]
	v_mfma_f32_16x16x32_bf16 v[74:77], v[138:141], v[208:211], v[74:77]
	v_mfma_f32_16x16x32_bf16 v[126:129], v[134:137], v[168:171], v[126:129]
	v_mfma_f32_16x16x32_bf16 v[122:125], v[142:145], v[168:171], v[122:125]
	v_mfma_f32_16x16x32_bf16 v[110:113], v[134:137], v[176:179], v[110:113]
	v_mfma_f32_16x16x32_bf16 v[106:109], v[142:145], v[176:179], v[106:109]
	v_mfma_f32_16x16x32_bf16 v[94:97], v[134:137], v[184:187], v[94:97]
	v_mfma_f32_16x16x32_bf16 v[90:93], v[142:145], v[184:187], v[90:93]
	v_mfma_f32_16x16x32_bf16 v[78:81], v[134:137], v[212:215], v[78:81]
	v_mfma_f32_16x16x32_bf16 v[74:77], v[142:145], v[212:215], v[74:77]
	v_mfma_f32_16x16x32_bf16 v[118:121], v[148:151], v[164:167], v[118:121]
	v_mfma_f32_16x16x32_bf16 v[114:117], v[156:159], v[164:167], v[114:117]
	v_mfma_f32_16x16x32_bf16 v[102:105], v[148:151], v[172:175], v[102:105]
	v_mfma_f32_16x16x32_bf16 v[98:101], v[156:159], v[172:175], v[98:101]
	v_mfma_f32_16x16x32_bf16 v[86:89], v[148:151], v[180:183], v[86:89]
	v_mfma_f32_16x16x32_bf16 v[82:85], v[156:159], v[180:183], v[82:85]
	v_mfma_f32_16x16x32_bf16 v[70:73], v[148:151], v[208:211], v[70:73]
	v_mfma_f32_16x16x32_bf16 v[66:69], v[156:159], v[208:211], v[66:69]
	v_mfma_f32_16x16x32_bf16 v[118:121], v[152:155], v[168:171], v[118:121]
	v_mfma_f32_16x16x32_bf16 v[114:117], v[160:163], v[168:171], v[114:117]
	v_mfma_f32_16x16x32_bf16 v[102:105], v[152:155], v[176:179], v[102:105]
	v_mfma_f32_16x16x32_bf16 v[98:101], v[160:163], v[176:179], v[98:101]
	v_mfma_f32_16x16x32_bf16 v[86:89], v[152:155], v[184:187], v[86:89]
	v_mfma_f32_16x16x32_bf16 v[82:85], v[160:163], v[184:187], v[82:85]
	v_mfma_f32_16x16x32_bf16 v[70:73], v[152:155], v[212:215], v[70:73]
	v_mfma_f32_16x16x32_bf16 v[66:69], v[160:163], v[212:215], v[66:69]
	s_barrier
	s_add_u32 s20, s20, 0x80080
	s_addc_u32 s21, s21, 0
	s_add_u32 s46, s46, 0xfff80080
	s_addc_u32 s47, s47, -1
	s_add_i32 s2, s2, s29
	s_mov_b32 m0, s2
	ds_read_b128 v[164:167], v228 offset:49152
	ds_read_b128 v[168:171], v228 offset:50176
	ds_read_b128 v[172:175], v228 offset:51200
	ds_read_b128 v[176:179], v228 offset:52224
	ds_read_b128 v[180:183], v228 offset:53248
	ds_read_b128 v[184:187], v228 offset:54272
	ds_read_b128 v[208:211], v228 offset:55296
	ds_read_b128 v[212:215], v228 offset:56320
	global_load_lds_dwordx4 v0, s[46:47]
	s_add_i32 m0, s2, 0x2000
	s_add_i32 s2, s45, s29
	global_load_lds_dwordx4 v188, s[46:47]
	s_mov_b32 m0, s2
	s_nop 0
	global_load_lds_dwordx4 v0, s[20:21]
	s_add_i32 m0, s2, 0x2000
	s_nop 0
	global_load_lds_dwordx4 v188, s[20:21]
	s_waitcnt vmcnt(6)
	s_waitcnt lgkmcnt(0)
	s_barrier
	s_waitcnt lgkmcnt(0)
	v_mfma_f32_16x16x32_bf16 v[62:65], v[130:133], v[164:167], v[62:65]
	v_mfma_f32_16x16x32_bf16 v[58:61], v[138:141], v[164:167], v[58:61]
	v_mfma_f32_16x16x32_bf16 v[46:49], v[130:133], v[172:175], v[46:49]
	v_mfma_f32_16x16x32_bf16 v[42:45], v[138:141], v[172:175], v[42:45]
	v_mfma_f32_16x16x32_bf16 v[30:33], v[130:133], v[180:183], v[30:33]
	v_mfma_f32_16x16x32_bf16 v[26:29], v[138:141], v[180:183], v[26:29]
	v_mfma_f32_16x16x32_bf16 v[14:17], v[130:133], v[208:211], v[14:17]
	v_mfma_f32_16x16x32_bf16 v[10:13], v[138:141], v[208:211], v[10:13]
	v_mfma_f32_16x16x32_bf16 v[62:65], v[134:137], v[168:171], v[62:65]
	v_mfma_f32_16x16x32_bf16 v[58:61], v[142:145], v[168:171], v[58:61]
	v_mfma_f32_16x16x32_bf16 v[46:49], v[134:137], v[176:179], v[46:49]
	v_mfma_f32_16x16x32_bf16 v[42:45], v[142:145], v[176:179], v[42:45]
	v_mfma_f32_16x16x32_bf16 v[30:33], v[134:137], v[184:187], v[30:33]
	v_mfma_f32_16x16x32_bf16 v[26:29], v[142:145], v[184:187], v[26:29]
	v_mfma_f32_16x16x32_bf16 v[14:17], v[134:137], v[212:215], v[14:17]
	v_mfma_f32_16x16x32_bf16 v[10:13], v[142:145], v[212:215], v[10:13]
	v_mfma_f32_16x16x32_bf16 v[54:57], v[148:151], v[164:167], v[54:57]
	v_mfma_f32_16x16x32_bf16 v[50:53], v[156:159], v[164:167], v[50:53]
	v_mfma_f32_16x16x32_bf16 v[38:41], v[148:151], v[172:175], v[38:41]
	v_mfma_f32_16x16x32_bf16 v[34:37], v[156:159], v[172:175], v[34:37]
	v_mfma_f32_16x16x32_bf16 v[22:25], v[148:151], v[180:183], v[22:25]
	v_mfma_f32_16x16x32_bf16 v[18:21], v[156:159], v[180:183], v[18:21]
	v_mfma_f32_16x16x32_bf16 v[6:9], v[148:151], v[208:211], v[6:9]
	v_mfma_f32_16x16x32_bf16 v[2:5], v[156:159], v[208:211], v[2:5]
	v_mfma_f32_16x16x32_bf16 v[54:57], v[152:155], v[168:171], v[54:57]
	v_mfma_f32_16x16x32_bf16 v[50:53], v[160:163], v[168:171], v[50:53]
	v_mfma_f32_16x16x32_bf16 v[38:41], v[152:155], v[176:179], v[38:41]
	v_mfma_f32_16x16x32_bf16 v[34:37], v[160:163], v[176:179], v[34:37]
	v_mfma_f32_16x16x32_bf16 v[22:25], v[152:155], v[184:187], v[22:25]
	v_mfma_f32_16x16x32_bf16 v[18:21], v[160:163], v[184:187], v[18:21]
	v_mfma_f32_16x16x32_bf16 v[6:9], v[152:155], v[212:215], v[6:9]
	v_mfma_f32_16x16x32_bf16 v[2:5], v[160:163], v[212:215], v[2:5]
	s_barrier
	s_add_i32 s44, s44, 2
	s_add_u32 s22, s22, 0x100
	s_addc_u32 s23, s23, 0
	s_add_u32 s42, s42, 0x100
	s_addc_u32 s43, s43, 0
	s_cmp_gt_u32 s44, 29
	s_cbranch_scc0 .LBB0_1102
	s_nop 0
	v_lshl_or_b32 v210, s3, 8, v227
	v_lshl_add_u32 v224, s34, 8, v147
	v_ashrrev_i32_e32 v211, 31, v210
	v_lshlrev_b64 v[130:131], 1, v[210:211]
	v_ashrrev_i32_e32 v225, 31, v224
	v_lshl_add_u64 v[132:133], s[8:9], 0, v[130:131]
	v_lshlrev_b64 v[134:135], 12, v[224:225]
	v_lshl_add_u64 v[136:137], v[132:133], 0, v[134:135]
	global_load_dwordx4 v[240:243], v[136:137], off
	global_load_dwordx4 v[244:247], v[136:137], off offset:256
	v_or_b32_e32 v222, 16, v224
	v_or_b32_e32 v220, 32, v224
	v_or_b32_e32 v218, 48, v224
	v_add_u32_e32 v216, 0x80, v224
	v_add_u32_e32 v214, 0x90, v224
	v_add_u32_e32 v212, 0xa0, v224
	v_add_u32_e32 v208, 0xb0, v224
	v_ashrrev_i32_e32 v223, 31, v222
	v_ashrrev_i32_e32 v221, 31, v220
	v_ashrrev_i32_e32 v219, 31, v218
	v_ashrrev_i32_e32 v217, 31, v216
	v_ashrrev_i32_e32 v215, 31, v214
	v_ashrrev_i32_e32 v213, 31, v212
	v_ashrrev_i32_e32 v209, 31, v208
	v_lshlrev_b64 v[136:137], 12, v[222:223]
	v_lshlrev_b64 v[138:139], 12, v[220:221]
	v_lshlrev_b64 v[140:141], 12, v[218:219]
	v_lshlrev_b64 v[142:143], 12, v[216:217]
	v_lshlrev_b64 v[144:145], 12, v[214:215]
	v_lshlrev_b64 v[148:149], 12, v[212:213]
	v_lshlrev_b64 v[150:151], 12, v[208:209]
	v_lshl_add_u64 v[134:135], s[8:9], 0, v[134:135]
	v_lshl_add_u64 v[136:137], v[132:133], 0, v[136:137]
	v_lshl_add_u64 v[138:139], v[132:133], 0, v[138:139]
	v_lshl_add_u64 v[140:141], v[132:133], 0, v[140:141]
	v_lshl_add_u64 v[142:143], v[132:133], 0, v[142:143]
	v_lshl_add_u64 v[144:145], v[132:133], 0, v[144:145]
	v_lshl_add_u64 v[236:237], v[132:133], 0, v[148:149]
	v_lshl_add_u64 v[132:133], v[132:133], 0, v[150:151]
	v_lshl_add_u64 v[248:249], v[134:135], 0, v[130:131]
	global_load_dwordx4 v[184:187], v[136:137], off
	global_load_dwordx4 v[180:183], v[136:137], off offset:256
	global_load_dwordx4 v[176:179], v[138:139], off
	global_load_dwordx4 v[172:175], v[138:139], off offset:256
	global_load_dwordx4 v[168:171], v[140:141], off
	global_load_dwordx4 v[164:167], v[140:141], off offset:256
	global_load_dwordx4 v[160:163], v[142:143], off
	global_load_dwordx4 v[156:159], v[142:143], off offset:256
	global_load_dwordx4 v[152:155], v[144:145], off
	global_load_dwordx4 v[148:151], v[144:145], off offset:256
	s_nop 0
	global_load_dwordx4 v[142:145], v[236:237], off
	global_load_dwordx4 v[138:141], v[236:237], off offset:256
	global_load_dwordx4 v[134:137], v[132:133], off
	s_nop 0
	global_load_dwordx4 v[130:133], v[132:133], off offset:256
	s_lshl_b32 s20, s3, 2
	s_ashr_i32 s21, s20, 31
	s_waitcnt vmcnt(0)
	v_lshlrev_b32_e32 v236, 16, v240
	v_and_b32_e32 v237, 0xffff0000, v240
	v_lshlrev_b32_e32 v250, 16, v242
	v_and_b32_e32 v251, 0xffff0000, v242
	v_lshlrev_b32_e32 v242, 16, v243
	v_and_b32_e32 v243, 0xffff0000, v243
	v_lshlrev_b32_e32 v240, 16, v241
	v_and_b32_e32 v241, 0xffff0000, v241
	v_pk_add_f32 v[126:127], v[126:127], v[236:237]
	v_pk_add_f32 v[236:237], v[124:125], v[242:243]
	v_pk_add_f32 v[124:125], v[122:123], v[250:251]
	v_pk_add_f32 v[128:129], v[128:129], v[240:241]
	v_cvt_pk_bf16_f32 v122, v126, v127
	v_lshlrev_b32_e32 v252, 16, v244
	v_cvt_pk_bf16_f32 v123, v128, v129
	v_cvt_pk_bf16_f32 v124, v124, v125
	v_cvt_pk_bf16_f32 v125, v236, v237
	global_store_dwordx4 v[248:249], v[122:125], off
	v_lshlrev_b32_e32 v126, 16, v122
	v_lshlrev_b32_e32 v127, 16, v123
	v_and_b32_e32 v122, 0xffff0000, v122
	v_and_b32_e32 v123, 0xffff0000, v123
	v_lshlrev_b32_e32 v128, 16, v124
	v_and_b32_e32 v124, 0xffff0000, v124
	v_lshlrev_b32_e32 v129, 16, v125
	v_and_b32_e32 v125, 0xffff0000, v125
	v_mul_f32_e32 v122, v122, v122
	v_mul_f32_e32 v123, v123, v123
	v_mul_f32_e32 v124, v124, v124
	v_mul_f32_e32 v125, v125, v125
	v_fmac_f32_e32 v122, v126, v126
	v_fmac_f32_e32 v123, v127, v127
	v_fmac_f32_e32 v124, v128, v128
	v_fmac_f32_e32 v125, v129, v129
	v_add_f32_e32 v122, v122, v123
	v_add_f32_e32 v123, v124, v125
	v_and_b32_e32 v253, 0xffff0000, v244
	v_add_f32_e32 v128, v122, v123
	v_lshlrev_b32_e32 v122, 16, v245
	v_and_b32_e32 v123, 0xffff0000, v245
	v_lshlrev_b32_e32 v124, 16, v246
	v_and_b32_e32 v125, 0xffff0000, v246
	v_lshlrev_b32_e32 v126, 16, v247
	v_and_b32_e32 v127, 0xffff0000, v247
	v_pk_add_f32 v[120:121], v[120:121], v[122:123]
	v_pk_add_f32 v[118:119], v[118:119], v[252:253]
	v_pk_add_f32 v[122:123], v[116:117], v[126:127]
	v_pk_add_f32 v[116:117], v[114:115], v[124:125]
	v_cvt_pk_bf16_f32 v114, v118, v119
	v_cvt_pk_bf16_f32 v115, v120, v121
	s_nop 0
	v_cvt_pk_bf16_f32 v116, v116, v117
	v_cvt_pk_bf16_f32 v117, v122, v123
	global_store_dwordx4 v[248:249], v[114:117], off offset:256
	v_lshlrev_b32_e32 v118, 16, v114
	v_lshlrev_b32_e32 v119, 16, v115
	v_and_b32_e32 v114, 0xffff0000, v114
	v_and_b32_e32 v115, 0xffff0000, v115
	v_mul_f32_e32 v114, v114, v114
	v_mul_f32_e32 v115, v115, v115
	v_lshlrev_b32_e32 v120, 16, v116
	v_and_b32_e32 v116, 0xffff0000, v116
	v_lshlrev_b32_e32 v121, 16, v117
	v_and_b32_e32 v117, 0xffff0000, v117
	v_fmac_f32_e32 v114, v118, v118
	v_fmac_f32_e32 v115, v119, v119
	v_add_f32_e32 v114, v114, v115
	v_mul_f32_e32 v115, v116, v116
	v_mul_f32_e32 v116, v117, v117
	v_fmac_f32_e32 v115, v120, v120
	v_fmac_f32_e32 v116, v121, v121
	v_add_f32_e32 v115, v115, v116
	v_add_f32_e32 v114, v114, v115
	s_mov_b32 s2, 0
	v_add_f32_e32 v114, v128, v114
	v_mbcnt_lo_u32_b32 v115, -1, s2
	v_mbcnt_hi_u32_b32 v115, -1, v115
	v_lshlrev_b32_e32 v115, 2, v115
	v_xor_b32_e32 v115, 64, v115
	ds_bpermute_b32 v115, v115, v114
	s_mov_b32 s2, 0
	s_waitcnt lgkmcnt(0)
	v_add_f32_e32 v114, v114, v115
	v_mbcnt_lo_u32_b32 v115, -1, s2
	v_mbcnt_hi_u32_b32 v115, -1, v115
	v_lshlrev_b32_e32 v115, 2, v115
	v_xor_b32_e32 v115, 0x80, v115
	ds_bpermute_b32 v115, v115, v114
	s_and_saveexec_b64 s[22:23], s[4:5]
	s_cbranch_execz .LBB0_1105
	v_lshlrev_b64 v[116:117], 7, v[224:225]
	v_lshl_add_u64 v[116:117], s[10:11], 0, v[116:117]
	v_lshl_add_u64 v[116:117], s[20:21], 2, v[116:117]
	s_lshl_b32 s50, s37, 2
	v_lshl_add_u64 v[116:117], v[116:117], 0, s[50:51]
	s_waitcnt lgkmcnt(0)
	v_add_f32_e32 v114, v114, v115
	global_store_dword v[116:117], v114, off
